# L2 touch of the following split-K unit's sample-row A block, each workgroup its 1/32 share, at the start of the last tile's epilogue (G2, G3a, G4, G6)
# baseline (speedup 1.0000x reference)
; __device__ __forceinline__ unsigned pk2(float lo, float hi) { return pg8::cvt_pk_bf16(lo, hi); }
; __device__ __forceinline__ float sigm(float x) { return __builtin_amdgcn_rcpf(1.f + __builtin_amdgcn_exp2f(-LOG2E * x)); }
; __device__ __forceinline__ void unpack8(const u32x4 w, float (&f)[8]) { f[0] = bflo(w.x); f[1] = bfhi(w.x); f[2] = bflo(w.y); f[3] = bfhi(w.y); f[4] = bflo(w.z); f[5] = bfhi(w.z); f[6] = bflo(w.w); f[7] = bfhi(w.w); }
;     __device__ __forceinline__ void operator()(const f32x4 (&acc)[2][2][4][2], const Unit& u, int wr, int wc, int fr, int fq) const {
;         const int row0 = u.pm * 256 + wr * 64 + fr, col0 = u.pn * 256 + wc * 32 + 8 * fq;
;         f32x4 bv[2][2];
; #pragma unroll
;         for (int bj = 0; bj < 2; ++bj)
; #pragma unroll
;             for (int n = 0; n < 2; ++n) bv[bj][n] = *(const f32x4*)(b + col0 + bj * 128 + 4 * n);
; #pragma unroll
;         for (int ai = 0; ai < 2; ++ai) {
;             u32x4 yraw[4][2];
; #pragma unroll
;             for (int m = 0; m < 4; ++m)
; #pragma unroll
;                 for (int bj = 0; bj < 2; ++bj) yraw[m][bj] = *(const u32x4*)(Y + (size_t)(row0 + ai * 128 + m * 16) * 512 + col0 + bj * 128);
;             __builtin_amdgcn_sched_barrier(0);
; #pragma unroll
;             for (int m = 0; m < 4; ++m) { const size_t off = (size_t)(row0 + ai * 128 + m * 16) * 512 + col0;
; #pragma unroll
;                 for (int bj = 0; bj < 2; ++bj) { const f32x4 v0 = acc[ai][bj][m][0] + bv[bj][0], v1 = acc[ai][bj][m][1] + bv[bj][1];
;                     float y[8]; unpack8(yraw[m][bj], y);
;                     u32x4 w; w.x = pk2(y[0] * sigm(v0[0]), y[1] * sigm(v0[1])); w.y = pk2(y[2] * sigm(v0[2]), y[3] * sigm(v0[3]));
;                     w.z = pk2(y[4] * sigm(v1[0]), y[5] * sigm(v1[1])); w.w = pk2(y[6] * sigm(v1[2]), y[7] * sigm(v1[3]));
;                     *(u32x4*)(O + off + bj * 128) = w; } } }
.LBB0_562:
	v_lshl_or_b32 v164, s28, 8, v222
	v_ashrrev_i32_e32 v165, 31, v164
	v_lshl_add_u32 v166, s63, 8, v220
	v_lshlrev_b64 v[198:199], 1, v[164:165]
	v_ashrrev_i32_e32 v167, 31, v166
	v_lshl_add_u64 v[200:201], s[46:47], 0, v[198:199]
	v_lshlrev_b64 v[202:203], 10, v[166:167]
	v_lshl_add_u64 v[96:97], v[164:165], 2, s[8:9]
	v_lshl_add_u64 v[164:165], v[200:201], 0, v[202:203]
	global_load_dwordx4 v[108:111], v[96:97], off offset:16
	global_load_dwordx4 v[112:115], v[96:97], off
	global_load_dwordx4 v[92:95], v[96:97], off offset:528
	s_nop 0
	global_load_dwordx4 v[96:99], v[96:97], off offset:512
	s_nop 0
	global_load_dwordx4 v[224:227], v[164:165], off
	global_load_dwordx4 v[228:231], v[164:165], off offset:256
	v_or_b32_e32 v164, 16, v166
	v_ashrrev_i32_e32 v165, 31, v164
	v_lshlrev_b64 v[208:209], 10, v[164:165]
	v_lshl_add_u64 v[164:165], v[200:201], 0, v[208:209]
	global_load_dwordx4 v[232:235], v[164:165], off
	global_load_dwordx4 v[180:183], v[164:165], off offset:256
	v_or_b32_e32 v164, 32, v166
	v_ashrrev_i32_e32 v165, 31, v164
	v_lshlrev_b64 v[206:207], 10, v[164:165]
	v_lshl_add_u64 v[164:165], v[200:201], 0, v[206:207]
	global_load_dwordx4 v[176:179], v[164:165], off
	global_load_dwordx4 v[172:175], v[164:165], off offset:256
	v_or_b32_e32 v164, 48, v166
	v_ashrrev_i32_e32 v165, 31, v164
	v_lshlrev_b64 v[204:205], 10, v[164:165]
	v_lshl_add_u64 v[164:165], v[200:201], 0, v[204:205]
	global_load_dwordx4 v[168:171], v[164:165], off
	s_cmp_lg_u64 s[6:7], 0
	s_cbranch_scc1 .Lskpf_g2
	s_and_b32 s98, s2, 7
	s_lshl_b32 s98, s98, 16
	s_add_u32 s98, s98, 0x7a80000
	s_lshr_b32 s99, s2, 3
	s_and_b32 s99, s99, 31
	s_lshl_b32 s99, s99, 12
	s_add_u32 s98, s98, s99
	s_add_u32 s98, s70, s98
	s_addc_u32 s99, s71, 0
	v_and_b32_e32 v240, 31, v184
	v_lshlrev_b32_e32 v240, 7, v240
	v_mov_b32_e32 v241, 0
	v_lshl_add_u64 v[240:241], s[98:99], 0, v[240:241]
	global_load_dword v242, v[240:241], off
.Lskpf_g2:
	s_nop 0
	global_load_dwordx4 v[164:167], v[164:165], off offset:256
	s_waitcnt vmcnt(0)
	v_pk_add_f32 v[160:161], v[160:161], v[112:113]
	v_pk_add_f32 v[162:163], v[162:163], v[114:115]
	v_mul_f32_e32 v160, 0xbfb8aa3b, v160
	v_exp_f32_e32 v160, v160
	v_mul_f32_e32 v161, 0xbfb8aa3b, v161
	v_exp_f32_e32 v161, v161
	v_pk_add_f32 v[236:237], v[156:157], v[108:109]
	v_add_f32_e32 v160, 1.0, v160
	v_rcp_f32_e32 v160, v160
	v_add_f32_e32 v161, 1.0, v161
	v_rcp_f32_e32 v161, v161
	v_lshlrev_b32_e32 v156, 16, v224
	v_and_b32_e32 v157, 0xffff0000, v224
	v_mul_f32_e32 v162, 0xbfb8aa3b, v162
	v_mul_f32_e32 v156, v160, v156
	v_mul_f32_e32 v160, 0xbfb8aa3b, v163
	v_exp_f32_e32 v162, v162
	v_mul_f32_e32 v157, v161, v157
	v_exp_f32_e32 v160, v160
	v_mul_f32_e32 v161, 0xbfb8aa3b, v236
	v_exp_f32_e32 v161, v161
	v_pk_add_f32 v[158:159], v[158:159], v[110:111]
	v_cvt_pk_bf16_f32 v156, v156, v157
	v_add_f32_e32 v157, 1.0, v162
	v_add_f32_e32 v160, 1.0, v160
	v_rcp_f32_e32 v157, v157
	v_rcp_f32_e32 v160, v160
	v_add_f32_e32 v161, 1.0, v161
	v_mul_f32_e32 v162, 0xbfb8aa3b, v237
	v_mul_f32_e32 v158, 0xbfb8aa3b, v158
	v_rcp_f32_e32 v161, v161
	v_exp_f32_e32 v162, v162
	v_exp_f32_e32 v158, v158
	v_mul_f32_e32 v159, 0xbfb8aa3b, v159
	v_exp_f32_e32 v159, v159
	v_lshlrev_b32_e32 v186, 16, v225
	v_and_b32_e32 v187, 0xffff0000, v225
	v_lshlrev_b32_e32 v210, 16, v226
	v_mul_f32_e32 v157, v157, v186
	v_mul_f32_e32 v160, v160, v187
	v_pk_add_f32 v[152:153], v[152:153], v[96:97]
	v_cvt_pk_bf16_f32 v157, v157, v160
	v_mul_f32_e32 v160, v161, v210
	v_add_f32_e32 v161, 1.0, v162
	v_add_f32_e32 v158, 1.0, v158
	v_mul_f32_e32 v152, 0xbfb8aa3b, v152
	v_rcp_f32_e32 v161, v161
	v_rcp_f32_e32 v162, v158
	v_add_f32_e32 v158, 1.0, v159
	v_exp_f32_e32 v152, v152
	v_mul_f32_e32 v153, 0xbfb8aa3b, v153
	v_rcp_f32_e32 v159, v158
	v_exp_f32_e32 v153, v153
	v_and_b32_e32 v211, 0xffff0000, v226
	v_lshlrev_b32_e32 v224, 16, v227
	v_and_b32_e32 v225, 0xffff0000, v227
	v_mul_f32_e32 v158, v161, v211
	v_add_f32_e32 v152, 1.0, v152
	v_cvt_pk_bf16_f32 v158, v160, v158
	v_mul_f32_e32 v160, v162, v224
	v_mul_f32_e32 v159, v159, v225
	v_rcp_f32_e32 v152, v152
	v_add_f32_e32 v153, 1.0, v153
	v_cvt_pk_bf16_f32 v159, v160, v159
	v_lshl_add_u64 v[160:161], s[50:51], 0, v[202:203]
	v_rcp_f32_e32 v153, v153
	v_lshl_add_u64 v[160:161], v[160:161], 0, v[198:199]
	global_store_dwordx4 v[160:161], v[156:159], off
	v_pk_add_f32 v[154:155], v[154:155], v[98:99]
	v_pk_add_f32 v[150:151], v[150:151], v[94:95]
	v_pk_add_f32 v[156:157], v[148:149], v[92:93]
	v_lshlrev_b32_e32 v148, 16, v228
	v_and_b32_e32 v149, 0xffff0000, v228
	v_mul_f32_e32 v154, 0xbfb8aa3b, v154
	v_mul_f32_e32 v148, v152, v148
	v_mul_f32_e32 v152, 0xbfb8aa3b, v155
	v_exp_f32_e32 v154, v154
	v_mul_f32_e32 v149, v153, v149
	v_exp_f32_e32 v152, v152
	v_mul_f32_e32 v153, 0xbfb8aa3b, v156
	v_exp_f32_e32 v153, v153
	v_cvt_pk_bf16_f32 v148, v148, v149
	v_add_f32_e32 v149, 1.0, v154
	v_add_f32_e32 v152, 1.0, v152
	v_mul_f32_e32 v150, 0xbfb8aa3b, v150
	v_rcp_f32_e32 v149, v149
	v_rcp_f32_e32 v152, v152
	v_add_f32_e32 v153, 1.0, v153
	v_mul_f32_e32 v154, 0xbfb8aa3b, v157
	v_exp_f32_e32 v150, v150
	v_mul_f32_e32 v151, 0xbfb8aa3b, v151
	v_rcp_f32_e32 v153, v153
	v_exp_f32_e32 v154, v154
	v_exp_f32_e32 v151, v151
	v_pk_add_f32 v[144:145], v[144:145], v[112:113]
	v_lshlrev_b32_e32 v158, 16, v229
	v_mul_f32_e32 v144, 0xbfb8aa3b, v144
	v_and_b32_e32 v159, 0xffff0000, v229
	v_exp_f32_e32 v144, v144
	v_mul_f32_e32 v145, 0xbfb8aa3b, v145
	v_lshlrev_b32_e32 v162, 16, v230
	v_mul_f32_e32 v149, v149, v158
	v_mul_f32_e32 v152, v152, v159
	v_add_f32_e32 v150, 1.0, v150
	v_exp_f32_e32 v145, v145
	v_cvt_pk_bf16_f32 v149, v149, v152
	v_mul_f32_e32 v152, v153, v162
; __device__ __forceinline__ unsigned pk2(float lo, float hi) { return pg8::cvt_pk_bf16(lo, hi); }
; __device__ __forceinline__ float sigm(float x) { return __builtin_amdgcn_rcpf(1.f + __builtin_amdgcn_exp2f(-LOG2E * x)); }
; __device__ __forceinline__ void unpack8(const u32x4 w, float (&f)[8]) { f[0] = bflo(w.x); f[1] = bfhi(w.x); f[2] = bflo(w.y); f[3] = bfhi(w.y); f[4] = bflo(w.z); f[5] = bfhi(w.z); f[6] = bflo(w.w); f[7] = bfhi(w.w); }
;     __device__ __forceinline__ void operator()(const f32x4 (&acc)[2][2][4][2], const Unit& u, int wr, int wc, int fr, int fq) const {
;     ...
;             for (int m = 0; m < 4; ++m) { const size_t off = (size_t)(row0 + ai * 128 + m * 16) * 512 + col0;
; #pragma unroll
;                 for (int bj = 0; bj < 2; ++bj) { const f32x4 v0 = acc[ai][bj][m][0] + bv[bj][0], v1 = acc[ai][bj][m][1] + bv[bj][1];
;                     float y[8]; unpack8(yraw[m][bj], y);
;                     u32x4 w; w.x = pk2(y[0] * sigm(v0[0]), y[1] * sigm(v0[1])); w.y = pk2(y[2] * sigm(v0[2]), y[3] * sigm(v0[3]));
;                     w.z = pk2(y[4] * sigm(v1[0]), y[5] * sigm(v1[1])); w.w = pk2(y[6] * sigm(v1[2]), y[7] * sigm(v1[3]));
;                     *(u32x4*)(O + off + bj * 128) = w; } } }
	v_add_f32_e32 v153, 1.0, v154
	v_rcp_f32_e32 v154, v150
	v_add_f32_e32 v150, 1.0, v151
	v_rcp_f32_e32 v153, v153
	v_rcp_f32_e32 v151, v150
	v_add_f32_e32 v144, 1.0, v144
	v_rcp_f32_e32 v144, v144
	v_add_f32_e32 v145, 1.0, v145
	v_and_b32_e32 v163, 0xffff0000, v230
	v_and_b32_e32 v187, 0xffff0000, v231
	v_rcp_f32_e32 v145, v145
	v_lshlrev_b32_e32 v186, 16, v231
	v_mul_f32_e32 v150, v153, v163
	v_mul_f32_e32 v151, v151, v187
	v_cvt_pk_bf16_f32 v150, v152, v150
	v_mul_f32_e32 v152, v154, v186
	v_cvt_pk_bf16_f32 v151, v152, v151
	global_store_dwordx4 v[160:161], v[148:151], off offset:256
	v_pk_add_f32 v[146:147], v[146:147], v[114:115]
	v_pk_add_f32 v[142:143], v[142:143], v[110:111]
	v_pk_add_f32 v[148:149], v[140:141], v[108:109]
	v_lshlrev_b32_e32 v140, 16, v232
	v_and_b32_e32 v141, 0xffff0000, v232
	v_mul_f32_e32 v146, 0xbfb8aa3b, v146
	v_mul_f32_e32 v140, v144, v140
	v_mul_f32_e32 v144, 0xbfb8aa3b, v147
	v_exp_f32_e32 v146, v146
	v_mul_f32_e32 v141, v145, v141
	v_exp_f32_e32 v144, v144
	v_mul_f32_e32 v145, 0xbfb8aa3b, v148
	v_exp_f32_e32 v145, v145
	v_cvt_pk_bf16_f32 v140, v140, v141
	v_add_f32_e32 v141, 1.0, v146
	v_add_f32_e32 v144, 1.0, v144
	v_rcp_f32_e32 v141, v141
	v_rcp_f32_e32 v144, v144
	v_add_f32_e32 v145, 1.0, v145
	v_mul_f32_e32 v146, 0xbfb8aa3b, v149
	v_mul_f32_e32 v142, 0xbfb8aa3b, v142
	v_rcp_f32_e32 v145, v145
	v_exp_f32_e32 v146, v146
	v_exp_f32_e32 v142, v142
	v_mul_f32_e32 v143, 0xbfb8aa3b, v143
	v_exp_f32_e32 v143, v143
	v_lshlrev_b32_e32 v150, 16, v233
	v_and_b32_e32 v151, 0xffff0000, v233
	v_lshlrev_b32_e32 v152, 16, v234
	v_mul_f32_e32 v141, v141, v150
	v_mul_f32_e32 v144, v144, v151
	v_pk_add_f32 v[136:137], v[136:137], v[96:97]
	v_cvt_pk_bf16_f32 v141, v141, v144
	v_mul_f32_e32 v144, v145, v152
	v_add_f32_e32 v145, 1.0, v146
	v_add_f32_e32 v142, 1.0, v142
	v_mul_f32_e32 v136, 0xbfb8aa3b, v136
	v_rcp_f32_e32 v145, v145
	v_rcp_f32_e32 v146, v142
	v_add_f32_e32 v142, 1.0, v143
	v_exp_f32_e32 v136, v136
	v_mul_f32_e32 v137, 0xbfb8aa3b, v137
	v_rcp_f32_e32 v143, v142
	v_exp_f32_e32 v137, v137
	v_and_b32_e32 v153, 0xffff0000, v234
	v_lshlrev_b32_e32 v154, 16, v235
	v_and_b32_e32 v155, 0xffff0000, v235
	v_mul_f32_e32 v142, v145, v153
	v_add_f32_e32 v136, 1.0, v136
	v_cvt_pk_bf16_f32 v142, v144, v142
	v_mul_f32_e32 v144, v146, v154
	v_mul_f32_e32 v143, v143, v155
	v_rcp_f32_e32 v136, v136
	v_add_f32_e32 v137, 1.0, v137
	v_cvt_pk_bf16_f32 v143, v144, v143
	v_lshl_add_u64 v[144:145], s[50:51], 0, v[208:209]
	v_rcp_f32_e32 v137, v137
	v_lshl_add_u64 v[144:145], v[144:145], 0, v[198:199]
	global_store_dwordx4 v[144:145], v[140:143], off
	v_pk_add_f32 v[138:139], v[138:139], v[98:99]
	v_pk_add_f32 v[134:135], v[134:135], v[94:95]
	v_pk_add_f32 v[140:141], v[132:133], v[92:93]
	v_lshlrev_b32_e32 v132, 16, v180
	v_and_b32_e32 v133, 0xffff0000, v180
	v_mul_f32_e32 v138, 0xbfb8aa3b, v138
	v_mul_f32_e32 v132, v136, v132
	v_mul_f32_e32 v136, 0xbfb8aa3b, v139
	v_exp_f32_e32 v138, v138
	v_mul_f32_e32 v133, v137, v133
	v_exp_f32_e32 v136, v136
	v_mul_f32_e32 v137, 0xbfb8aa3b, v140
	v_exp_f32_e32 v137, v137
	v_cvt_pk_bf16_f32 v132, v132, v133
	v_add_f32_e32 v133, 1.0, v138
	v_add_f32_e32 v136, 1.0, v136
	v_mul_f32_e32 v134, 0xbfb8aa3b, v134
	v_rcp_f32_e32 v133, v133
	v_rcp_f32_e32 v136, v136
	v_add_f32_e32 v137, 1.0, v137
	v_mul_f32_e32 v138, 0xbfb8aa3b, v141
	v_exp_f32_e32 v134, v134
	v_mul_f32_e32 v135, 0xbfb8aa3b, v135
	v_rcp_f32_e32 v137, v137
	v_exp_f32_e32 v138, v138
	v_exp_f32_e32 v135, v135
	v_pk_add_f32 v[128:129], v[128:129], v[112:113]
	v_lshlrev_b32_e32 v142, 16, v181
	v_mul_f32_e32 v128, 0xbfb8aa3b, v128
	v_and_b32_e32 v143, 0xffff0000, v181
	v_exp_f32_e32 v128, v128
	v_mul_f32_e32 v129, 0xbfb8aa3b, v129
	v_lshlrev_b32_e32 v146, 16, v182
	v_mul_f32_e32 v133, v133, v142
	v_mul_f32_e32 v136, v136, v143
	v_add_f32_e32 v134, 1.0, v134
	v_exp_f32_e32 v129, v129
	v_cvt_pk_bf16_f32 v133, v133, v136
	v_mul_f32_e32 v136, v137, v146
	v_add_f32_e32 v137, 1.0, v138
	v_rcp_f32_e32 v138, v134
	v_add_f32_e32 v134, 1.0, v135
	v_rcp_f32_e32 v137, v137
	v_rcp_f32_e32 v135, v134
	v_add_f32_e32 v128, 1.0, v128
	v_rcp_f32_e32 v128, v128
	v_add_f32_e32 v129, 1.0, v129
	v_and_b32_e32 v147, 0xffff0000, v182
	v_and_b32_e32 v149, 0xffff0000, v183
	v_rcp_f32_e32 v129, v129
	v_lshlrev_b32_e32 v148, 16, v183
	v_mul_f32_e32 v134, v137, v147
	v_mul_f32_e32 v135, v135, v149
	v_cvt_pk_bf16_f32 v134, v136, v134
	v_mul_f32_e32 v136, v138, v148
	v_cvt_pk_bf16_f32 v135, v136, v135
	global_store_dwordx4 v[144:145], v[132:135], off offset:256
	v_pk_add_f32 v[130:131], v[130:131], v[114:115]
	v_pk_add_f32 v[126:127], v[126:127], v[110:111]
	v_pk_add_f32 v[132:133], v[124:125], v[108:109]
	v_lshlrev_b32_e32 v124, 16, v176
	v_and_b32_e32 v125, 0xffff0000, v176
	v_mul_f32_e32 v130, 0xbfb8aa3b, v130
	v_mul_f32_e32 v124, v128, v124
	v_mul_f32_e32 v128, 0xbfb8aa3b, v131
	v_exp_f32_e32 v130, v130
	v_mul_f32_e32 v125, v129, v125
	v_exp_f32_e32 v128, v128
	v_mul_f32_e32 v129, 0xbfb8aa3b, v132
	v_exp_f32_e32 v129, v129
	v_cvt_pk_bf16_f32 v124, v124, v125
	v_add_f32_e32 v125, 1.0, v130
	v_add_f32_e32 v128, 1.0, v128
	v_rcp_f32_e32 v125, v125
	v_rcp_f32_e32 v128, v128
	v_add_f32_e32 v129, 1.0, v129
	v_mul_f32_e32 v130, 0xbfb8aa3b, v133
	v_mul_f32_e32 v126, 0xbfb8aa3b, v126
	v_rcp_f32_e32 v129, v129
	v_exp_f32_e32 v130, v130
	v_exp_f32_e32 v126, v126
	v_mul_f32_e32 v127, 0xbfb8aa3b, v127
	v_exp_f32_e32 v127, v127
	v_lshlrev_b32_e32 v134, 16, v177
	v_and_b32_e32 v135, 0xffff0000, v177
	v_lshlrev_b32_e32 v136, 16, v178
	v_mul_f32_e32 v125, v125, v134
	v_mul_f32_e32 v128, v128, v135
	v_pk_add_f32 v[120:121], v[120:121], v[96:97]
	v_cvt_pk_bf16_f32 v125, v125, v128
; __device__ __forceinline__ unsigned pk2(float lo, float hi) { return pg8::cvt_pk_bf16(lo, hi); }
; __device__ __forceinline__ float sigm(float x) { return __builtin_amdgcn_rcpf(1.f + __builtin_amdgcn_exp2f(-LOG2E * x)); }
; __device__ __forceinline__ void unpack8(const u32x4 w, float (&f)[8]) { f[0] = bflo(w.x); f[1] = bfhi(w.x); f[2] = bflo(w.y); f[3] = bfhi(w.y); f[4] = bflo(w.z); f[5] = bfhi(w.z); f[6] = bflo(w.w); f[7] = bfhi(w.w); }
;     __device__ __forceinline__ void operator()(const f32x4 (&acc)[2][2][4][2], const Unit& u, int wr, int wc, int fr, int fq) const {
;     ...
;             for (int m = 0; m < 4; ++m) { const size_t off = (size_t)(row0 + ai * 128 + m * 16) * 512 + col0;
; #pragma unroll
;                 for (int bj = 0; bj < 2; ++bj) { const f32x4 v0 = acc[ai][bj][m][0] + bv[bj][0], v1 = acc[ai][bj][m][1] + bv[bj][1];
;                     float y[8]; unpack8(yraw[m][bj], y);
;                     u32x4 w; w.x = pk2(y[0] * sigm(v0[0]), y[1] * sigm(v0[1])); w.y = pk2(y[2] * sigm(v0[2]), y[3] * sigm(v0[3]));
;                     w.z = pk2(y[4] * sigm(v1[0]), y[5] * sigm(v1[1])); w.w = pk2(y[6] * sigm(v1[2]), y[7] * sigm(v1[3]));
;                     *(u32x4*)(O + off + bj * 128) = w; } } }
	v_mul_f32_e32 v128, v129, v136
	v_add_f32_e32 v129, 1.0, v130
	v_add_f32_e32 v126, 1.0, v126
	v_mul_f32_e32 v120, 0xbfb8aa3b, v120
	v_rcp_f32_e32 v129, v129
	v_rcp_f32_e32 v130, v126
	v_add_f32_e32 v126, 1.0, v127
	v_exp_f32_e32 v120, v120
	v_mul_f32_e32 v121, 0xbfb8aa3b, v121
	v_rcp_f32_e32 v127, v126
	v_exp_f32_e32 v121, v121
	v_and_b32_e32 v137, 0xffff0000, v178
	v_lshlrev_b32_e32 v138, 16, v179
	v_and_b32_e32 v139, 0xffff0000, v179
	v_mul_f32_e32 v126, v129, v137
	v_add_f32_e32 v120, 1.0, v120
	v_cvt_pk_bf16_f32 v126, v128, v126
	v_mul_f32_e32 v128, v130, v138
	v_mul_f32_e32 v127, v127, v139
	v_rcp_f32_e32 v120, v120
	v_add_f32_e32 v121, 1.0, v121
	v_cvt_pk_bf16_f32 v127, v128, v127
	v_lshl_add_u64 v[128:129], s[50:51], 0, v[206:207]
	v_rcp_f32_e32 v121, v121
	v_lshl_add_u64 v[128:129], v[128:129], 0, v[198:199]
	global_store_dwordx4 v[128:129], v[124:127], off
	v_pk_add_f32 v[122:123], v[122:123], v[98:99]
	v_pk_add_f32 v[118:119], v[118:119], v[94:95]
	v_pk_add_f32 v[124:125], v[116:117], v[92:93]
	v_lshlrev_b32_e32 v116, 16, v172
	v_and_b32_e32 v117, 0xffff0000, v172
	v_mul_f32_e32 v122, 0xbfb8aa3b, v122
	v_mul_f32_e32 v116, v120, v116
	v_mul_f32_e32 v120, 0xbfb8aa3b, v123
	v_exp_f32_e32 v122, v122
	v_mul_f32_e32 v117, v121, v117
	v_exp_f32_e32 v120, v120
	v_mul_f32_e32 v121, 0xbfb8aa3b, v124
	v_exp_f32_e32 v121, v121
	v_cvt_pk_bf16_f32 v116, v116, v117
	v_add_f32_e32 v117, 1.0, v122
	v_add_f32_e32 v120, 1.0, v120
	v_mul_f32_e32 v118, 0xbfb8aa3b, v118
	v_rcp_f32_e32 v117, v117
	v_rcp_f32_e32 v120, v120
	v_add_f32_e32 v121, 1.0, v121
	v_mul_f32_e32 v122, 0xbfb8aa3b, v125
	v_exp_f32_e32 v118, v118
	v_mul_f32_e32 v119, 0xbfb8aa3b, v119
	v_rcp_f32_e32 v121, v121
	v_exp_f32_e32 v122, v122
	v_exp_f32_e32 v119, v119
	v_pk_add_f32 v[104:105], v[104:105], v[112:113]
	v_lshlrev_b32_e32 v126, 16, v173
	v_mul_f32_e32 v104, 0xbfb8aa3b, v104
	v_and_b32_e32 v127, 0xffff0000, v173
	v_exp_f32_e32 v104, v104
	v_mul_f32_e32 v105, 0xbfb8aa3b, v105
	v_lshlrev_b32_e32 v130, 16, v174
	v_mul_f32_e32 v117, v117, v126
	v_mul_f32_e32 v120, v120, v127
	v_add_f32_e32 v118, 1.0, v118
	v_exp_f32_e32 v105, v105
	v_cvt_pk_bf16_f32 v117, v117, v120
	v_mul_f32_e32 v120, v121, v130
	v_add_f32_e32 v121, 1.0, v122
	v_rcp_f32_e32 v122, v118
	v_add_f32_e32 v118, 1.0, v119
	v_rcp_f32_e32 v121, v121
	v_rcp_f32_e32 v119, v118
	v_add_f32_e32 v104, 1.0, v104
	v_rcp_f32_e32 v104, v104
	v_add_f32_e32 v105, 1.0, v105
	v_and_b32_e32 v131, 0xffff0000, v174
	v_and_b32_e32 v133, 0xffff0000, v175
	v_rcp_f32_e32 v105, v105
	v_lshlrev_b32_e32 v132, 16, v175
	v_mul_f32_e32 v118, v121, v131
	v_mul_f32_e32 v119, v119, v133
	v_cvt_pk_bf16_f32 v118, v120, v118
	v_mul_f32_e32 v120, v122, v132
	v_cvt_pk_bf16_f32 v119, v120, v119
	global_store_dwordx4 v[128:129], v[116:119], off offset:256
	v_pk_add_f32 v[106:107], v[106:107], v[114:115]
	v_pk_add_f32 v[102:103], v[102:103], v[110:111]
	v_pk_add_f32 v[116:117], v[100:101], v[108:109]
	v_lshlrev_b32_e32 v100, 16, v168
	v_and_b32_e32 v101, 0xffff0000, v168
	v_mul_f32_e32 v106, 0xbfb8aa3b, v106
	v_mul_f32_e32 v100, v104, v100
	v_mul_f32_e32 v104, 0xbfb8aa3b, v107
	v_exp_f32_e32 v106, v106
	v_mul_f32_e32 v101, v105, v101
	v_exp_f32_e32 v104, v104
	v_mul_f32_e32 v105, 0xbfb8aa3b, v116
	v_exp_f32_e32 v105, v105
	v_cvt_pk_bf16_f32 v100, v100, v101
	v_add_f32_e32 v101, 1.0, v106
	v_add_f32_e32 v104, 1.0, v104
	v_rcp_f32_e32 v101, v101
	v_rcp_f32_e32 v104, v104
	v_add_f32_e32 v105, 1.0, v105
	v_mul_f32_e32 v106, 0xbfb8aa3b, v117
	v_mul_f32_e32 v102, 0xbfb8aa3b, v102
	v_rcp_f32_e32 v105, v105
	v_exp_f32_e32 v106, v106
	v_exp_f32_e32 v102, v102
	v_mul_f32_e32 v103, 0xbfb8aa3b, v103
	v_exp_f32_e32 v103, v103
	v_lshlrev_b32_e32 v118, 16, v169
	v_and_b32_e32 v119, 0xffff0000, v169
	v_lshlrev_b32_e32 v120, 16, v170
	v_mul_f32_e32 v101, v101, v118
	v_mul_f32_e32 v104, v104, v119
	v_pk_add_f32 v[88:89], v[88:89], v[96:97]
	v_cvt_pk_bf16_f32 v101, v101, v104
	v_mul_f32_e32 v104, v105, v120
	v_add_f32_e32 v105, 1.0, v106
	v_add_f32_e32 v102, 1.0, v102
	v_mul_f32_e32 v89, 0xbfb8aa3b, v89
	v_rcp_f32_e32 v105, v105
	v_rcp_f32_e32 v106, v102
	v_add_f32_e32 v102, 1.0, v103
	v_mul_f32_e32 v88, 0xbfb8aa3b, v88
	v_exp_f32_e32 v89, v89
	v_rcp_f32_e32 v103, v102
	v_exp_f32_e32 v88, v88
	v_and_b32_e32 v121, 0xffff0000, v170
	v_lshlrev_b32_e32 v122, 16, v171
	v_and_b32_e32 v123, 0xffff0000, v171
	v_mul_f32_e32 v102, v105, v121
	v_add_f32_e32 v89, 1.0, v89
	v_cvt_pk_bf16_f32 v102, v104, v102
	v_mul_f32_e32 v104, v106, v122
	v_mul_f32_e32 v103, v103, v123
	v_add_f32_e32 v88, 1.0, v88
	v_rcp_f32_e32 v89, v89
	v_cvt_pk_bf16_f32 v103, v104, v103
	v_lshl_add_u64 v[104:105], s[50:51], 0, v[204:205]
	v_rcp_f32_e32 v88, v88
	v_lshl_add_u64 v[142:143], v[104:105], 0, v[198:199]
	global_store_dwordx4 v[142:143], v[100:103], off
	v_pk_add_f32 v[84:85], v[84:85], v[92:93]
	v_pk_add_f32 v[90:91], v[90:91], v[98:99]
	v_and_b32_e32 v101, 0xffff0000, v164
	v_pk_add_f32 v[86:87], v[86:87], v[94:95]
	v_lshlrev_b32_e32 v100, 16, v164
	v_mul_f32_e32 v89, v89, v101
	v_mul_f32_e32 v84, 0xbfb8aa3b, v84
	v_mul_f32_e32 v85, 0xbfb8aa3b, v85
	v_mul_f32_e32 v90, 0xbfb8aa3b, v90
	v_mul_f32_e32 v88, v88, v100
	v_cvt_pk_bf16_f32 v126, v88, v89
	v_mul_f32_e32 v89, 0xbfb8aa3b, v91
	v_exp_f32_e32 v84, v84
	v_exp_f32_e32 v85, v85
	v_mul_f32_e32 v86, 0xbfb8aa3b, v86
	v_mul_f32_e32 v87, 0xbfb8aa3b, v87
	v_exp_f32_e32 v90, v90
	v_exp_f32_e32 v89, v89
	v_exp_f32_e32 v86, v86
	v_exp_f32_e32 v87, v87
	v_add_f32_e32 v84, 1.0, v84
	v_add_f32_e32 v85, 1.0, v85
	v_add_f32_e32 v88, 1.0, v90
	v_add_f32_e32 v89, 1.0, v89
	v_rcp_f32_e32 v84, v84
	v_rcp_f32_e32 v85, v85
	v_add_f32_e32 v86, 1.0, v86
	v_add_f32_e32 v87, 1.0, v87
; __device__ __forceinline__ unsigned pk2(float lo, float hi) { return pg8::cvt_pk_bf16(lo, hi); }
; __device__ __forceinline__ float sigm(float x) { return __builtin_amdgcn_rcpf(1.f + __builtin_amdgcn_exp2f(-LOG2E * x)); }
; __device__ __forceinline__ void unpack8(const u32x4 w, float (&f)[8]) { f[0] = bflo(w.x); f[1] = bfhi(w.x); f[2] = bflo(w.y); f[3] = bfhi(w.y); f[4] = bflo(w.z); f[5] = bfhi(w.z); f[6] = bflo(w.w); f[7] = bfhi(w.w); }
;     __device__ __forceinline__ void operator()(const f32x4 (&acc)[2][2][4][2], const Unit& u, int wr, int wc, int fr, int fq) const {
;     ...
;         for (int ai = 0; ai < 2; ++ai) {
;             u32x4 yraw[4][2];
; #pragma unroll
;             for (int m = 0; m < 4; ++m)
; #pragma unroll
;                 for (int bj = 0; bj < 2; ++bj) yraw[m][bj] = *(const u32x4*)(Y + (size_t)(row0 + ai * 128 + m * 16) * 512 + col0 + bj * 128);
;             __builtin_amdgcn_sched_barrier(0);
; #pragma unroll
;             for (int m = 0; m < 4; ++m) { const size_t off = (size_t)(row0 + ai * 128 + m * 16) * 512 + col0;
; #pragma unroll
;                 for (int bj = 0; bj < 2; ++bj) { const f32x4 v0 = acc[ai][bj][m][0] + bv[bj][0], v1 = acc[ai][bj][m][1] + bv[bj][1];
;                     float y[8]; unpack8(yraw[m][bj], y);
;                     u32x4 w; w.x = pk2(y[0] * sigm(v0[0]), y[1] * sigm(v0[1])); w.y = pk2(y[2] * sigm(v0[2]), y[3] * sigm(v0[3]));
;                     w.z = pk2(y[4] * sigm(v1[0]), y[5] * sigm(v1[1])); w.w = pk2(y[6] * sigm(v1[2]), y[7] * sigm(v1[3]));
;                     *(u32x4*)(O + off + bj * 128) = w; } } }
	v_rcp_f32_e32 v88, v88
	v_rcp_f32_e32 v89, v89
	v_rcp_f32_e32 v86, v86
	v_rcp_f32_e32 v87, v87
	v_lshlrev_b32_e32 v104, 16, v166
	v_and_b32_e32 v105, 0xffff0000, v166
	v_lshlrev_b32_e32 v102, 16, v165
	v_and_b32_e32 v103, 0xffff0000, v165
	v_lshlrev_b32_e32 v106, 16, v167
	v_and_b32_e32 v107, 0xffff0000, v167
	v_mul_f32_e32 v84, v84, v104
	v_mul_f32_e32 v85, v85, v105
	s_mov_b64 s[0:1], 0x20000
	v_mul_f32_e32 v88, v88, v102
	v_mul_f32_e32 v89, v89, v103
	v_cvt_pk_bf16_f32 v127, v88, v89
	v_cvt_pk_bf16_f32 v128, v84, v85
	v_mul_f32_e32 v84, v86, v106
	v_mul_f32_e32 v85, v87, v107
	v_lshl_add_u64 v[144:145], v[202:203], 0, s[0:1]
	s_mov_b64 s[0:1], 0x24000
	v_cvt_pk_bf16_f32 v129, v84, v85
	v_lshl_add_u64 v[84:85], v[200:201], 0, v[144:145]
	v_lshl_add_u64 v[124:125], v[202:203], 0, s[0:1]
	s_mov_b64 s[0:1], 0x28000
	global_load_dwordx4 v[130:133], v[84:85], off
	global_load_dwordx4 v[134:137], v[84:85], off offset:256
	v_lshl_add_u64 v[84:85], v[200:201], 0, v[124:125]
	v_lshl_add_u64 v[122:123], v[202:203], 0, s[0:1]
	s_mov_b64 s[0:1], 0x2c000
	global_load_dwordx4 v[138:141], v[84:85], off
	global_load_dwordx4 v[116:119], v[84:85], off offset:256
	v_lshl_add_u64 v[84:85], v[200:201], 0, v[122:123]
	v_lshl_add_u64 v[120:121], v[202:203], 0, s[0:1]
	global_load_dwordx4 v[104:107], v[84:85], off
	global_load_dwordx4 v[100:103], v[84:85], off offset:256
	v_lshl_add_u64 v[84:85], v[200:201], 0, v[120:121]
	global_load_dwordx4 v[88:91], v[84:85], off
	s_nop 0
	global_load_dwordx4 v[84:87], v[84:85], off offset:256
	s_nop 0
	global_store_dwordx4 v[142:143], v[126:129], off offset:256
	v_pk_add_f32 v[80:81], v[80:81], v[112:113]
	v_pk_add_f32 v[82:83], v[82:83], v[114:115]
	v_mul_f32_e32 v80, 0xbfb8aa3b, v80
	v_exp_f32_e32 v80, v80
	v_mul_f32_e32 v81, 0xbfb8aa3b, v81
	v_exp_f32_e32 v81, v81
	v_pk_add_f32 v[126:127], v[76:77], v[108:109]
	v_add_f32_e32 v80, 1.0, v80
	v_rcp_f32_e32 v80, v80
	v_add_f32_e32 v81, 1.0, v81
	v_rcp_f32_e32 v81, v81
	s_waitcnt vmcnt(8)
	v_lshlrev_b32_e32 v76, 16, v130
	v_and_b32_e32 v77, 0xffff0000, v130
	v_mul_f32_e32 v82, 0xbfb8aa3b, v82
	v_mul_f32_e32 v76, v80, v76
	v_mul_f32_e32 v80, 0xbfb8aa3b, v83
	v_exp_f32_e32 v82, v82
	v_mul_f32_e32 v77, v81, v77
	v_exp_f32_e32 v80, v80
	v_mul_f32_e32 v81, 0xbfb8aa3b, v126
	v_exp_f32_e32 v81, v81
	v_pk_add_f32 v[78:79], v[78:79], v[110:111]
	v_cvt_pk_bf16_f32 v76, v76, v77
	v_add_f32_e32 v77, 1.0, v82
	v_add_f32_e32 v80, 1.0, v80
	v_rcp_f32_e32 v77, v77
	v_rcp_f32_e32 v80, v80
	v_add_f32_e32 v81, 1.0, v81
	v_mul_f32_e32 v82, 0xbfb8aa3b, v127
	v_mul_f32_e32 v78, 0xbfb8aa3b, v78
	v_rcp_f32_e32 v81, v81
	v_exp_f32_e32 v82, v82
	v_exp_f32_e32 v78, v78
	v_mul_f32_e32 v79, 0xbfb8aa3b, v79
	v_exp_f32_e32 v79, v79
	v_lshlrev_b32_e32 v128, 16, v131
	v_and_b32_e32 v129, 0xffff0000, v131
	v_lshlrev_b32_e32 v130, 16, v132
	v_mul_f32_e32 v77, v77, v128
	v_mul_f32_e32 v80, v80, v129
	v_pk_add_f32 v[72:73], v[72:73], v[96:97]
	v_cvt_pk_bf16_f32 v77, v77, v80
	v_mul_f32_e32 v80, v81, v130
	v_add_f32_e32 v81, 1.0, v82
	v_add_f32_e32 v78, 1.0, v78
	v_mul_f32_e32 v72, 0xbfb8aa3b, v72
	v_rcp_f32_e32 v81, v81
	v_rcp_f32_e32 v82, v78
	v_add_f32_e32 v78, 1.0, v79
	v_exp_f32_e32 v72, v72
	v_mul_f32_e32 v73, 0xbfb8aa3b, v73
	v_rcp_f32_e32 v79, v78
	v_exp_f32_e32 v73, v73
	v_and_b32_e32 v131, 0xffff0000, v132
	v_lshlrev_b32_e32 v132, 16, v133
	v_and_b32_e32 v133, 0xffff0000, v133
	v_mul_f32_e32 v78, v81, v131
	v_add_f32_e32 v72, 1.0, v72
	v_cvt_pk_bf16_f32 v78, v80, v78
	v_mul_f32_e32 v80, v82, v132
	v_mul_f32_e32 v79, v79, v133
	v_rcp_f32_e32 v72, v72
	v_add_f32_e32 v73, 1.0, v73
	v_cvt_pk_bf16_f32 v79, v80, v79
	v_lshl_add_u64 v[80:81], s[50:51], 0, v[144:145]
	v_rcp_f32_e32 v73, v73
	v_lshl_add_u64 v[80:81], v[80:81], 0, v[198:199]
	global_store_dwordx4 v[80:81], v[76:79], off
	v_pk_add_f32 v[74:75], v[74:75], v[98:99]
	v_pk_add_f32 v[70:71], v[70:71], v[94:95]
	v_pk_add_f32 v[76:77], v[68:69], v[92:93]
	s_waitcnt vmcnt(8)
	v_lshlrev_b32_e32 v68, 16, v134
	v_and_b32_e32 v69, 0xffff0000, v134
	v_mul_f32_e32 v74, 0xbfb8aa3b, v74
	v_mul_f32_e32 v68, v72, v68
	v_mul_f32_e32 v72, 0xbfb8aa3b, v75
	v_exp_f32_e32 v74, v74
	v_mul_f32_e32 v69, v73, v69
	v_exp_f32_e32 v72, v72
	v_mul_f32_e32 v73, 0xbfb8aa3b, v76
	v_exp_f32_e32 v73, v73
	v_cvt_pk_bf16_f32 v68, v68, v69
	v_add_f32_e32 v69, 1.0, v74
	v_add_f32_e32 v72, 1.0, v72
	v_mul_f32_e32 v70, 0xbfb8aa3b, v70
	v_rcp_f32_e32 v69, v69
	v_rcp_f32_e32 v72, v72
	v_add_f32_e32 v73, 1.0, v73
	v_mul_f32_e32 v74, 0xbfb8aa3b, v77
	v_exp_f32_e32 v70, v70
	v_mul_f32_e32 v71, 0xbfb8aa3b, v71
	v_rcp_f32_e32 v73, v73
	v_exp_f32_e32 v74, v74
	v_exp_f32_e32 v71, v71
	v_pk_add_f32 v[64:65], v[64:65], v[112:113]
	v_lshlrev_b32_e32 v78, 16, v135
	v_mul_f32_e32 v64, 0xbfb8aa3b, v64
	v_and_b32_e32 v79, 0xffff0000, v135
	v_exp_f32_e32 v64, v64
	v_mul_f32_e32 v65, 0xbfb8aa3b, v65
	v_lshlrev_b32_e32 v82, 16, v136
	v_mul_f32_e32 v69, v69, v78
	v_mul_f32_e32 v72, v72, v79
	v_add_f32_e32 v70, 1.0, v70
	v_exp_f32_e32 v65, v65
	v_cvt_pk_bf16_f32 v69, v69, v72
	v_mul_f32_e32 v72, v73, v82
	v_add_f32_e32 v73, 1.0, v74
	v_rcp_f32_e32 v74, v70
	v_add_f32_e32 v70, 1.0, v71
	v_rcp_f32_e32 v73, v73
	v_rcp_f32_e32 v71, v70
	v_add_f32_e32 v64, 1.0, v64
	v_rcp_f32_e32 v64, v64
	v_add_f32_e32 v65, 1.0, v65
	v_and_b32_e32 v83, 0xffff0000, v136
	v_and_b32_e32 v127, 0xffff0000, v137
	v_rcp_f32_e32 v65, v65
	v_lshlrev_b32_e32 v126, 16, v137
	v_mul_f32_e32 v70, v73, v83
	v_mul_f32_e32 v71, v71, v127
	v_cvt_pk_bf16_f32 v70, v72, v70
	v_mul_f32_e32 v72, v74, v126
	v_cvt_pk_bf16_f32 v71, v72, v71
	global_store_dwordx4 v[80:81], v[68:71], off offset:256
	v_pk_add_f32 v[66:67], v[66:67], v[114:115]
	v_pk_add_f32 v[62:63], v[62:63], v[110:111]
	v_pk_add_f32 v[68:69], v[60:61], v[108:109]
	s_waitcnt vmcnt(8)
; __device__ __forceinline__ unsigned pk2(float lo, float hi) { return pg8::cvt_pk_bf16(lo, hi); }
; __device__ __forceinline__ float sigm(float x) { return __builtin_amdgcn_rcpf(1.f + __builtin_amdgcn_exp2f(-LOG2E * x)); }
; __device__ __forceinline__ void unpack8(const u32x4 w, float (&f)[8]) { f[0] = bflo(w.x); f[1] = bfhi(w.x); f[2] = bflo(w.y); f[3] = bfhi(w.y); f[4] = bflo(w.z); f[5] = bfhi(w.z); f[6] = bflo(w.w); f[7] = bfhi(w.w); }
;     __device__ __forceinline__ void operator()(const f32x4 (&acc)[2][2][4][2], const Unit& u, int wr, int wc, int fr, int fq) const {
;     ...
;             for (int m = 0; m < 4; ++m) { const size_t off = (size_t)(row0 + ai * 128 + m * 16) * 512 + col0;
; #pragma unroll
;                 for (int bj = 0; bj < 2; ++bj) { const f32x4 v0 = acc[ai][bj][m][0] + bv[bj][0], v1 = acc[ai][bj][m][1] + bv[bj][1];
;                     float y[8]; unpack8(yraw[m][bj], y);
;                     u32x4 w; w.x = pk2(y[0] * sigm(v0[0]), y[1] * sigm(v0[1])); w.y = pk2(y[2] * sigm(v0[2]), y[3] * sigm(v0[3]));
;                     w.z = pk2(y[4] * sigm(v1[0]), y[5] * sigm(v1[1])); w.w = pk2(y[6] * sigm(v1[2]), y[7] * sigm(v1[3]));
;                     *(u32x4*)(O + off + bj * 128) = w; } } }
	v_lshlrev_b32_e32 v60, 16, v138
	v_and_b32_e32 v61, 0xffff0000, v138
	v_mul_f32_e32 v66, 0xbfb8aa3b, v66
	v_mul_f32_e32 v60, v64, v60
	v_mul_f32_e32 v64, 0xbfb8aa3b, v67
	v_exp_f32_e32 v66, v66
	v_mul_f32_e32 v61, v65, v61
	v_exp_f32_e32 v64, v64
	v_mul_f32_e32 v65, 0xbfb8aa3b, v68
	v_exp_f32_e32 v65, v65
	v_cvt_pk_bf16_f32 v60, v60, v61
	v_add_f32_e32 v61, 1.0, v66
	v_add_f32_e32 v64, 1.0, v64
	v_rcp_f32_e32 v61, v61
	v_rcp_f32_e32 v64, v64
	v_add_f32_e32 v65, 1.0, v65
	v_mul_f32_e32 v66, 0xbfb8aa3b, v69
	v_mul_f32_e32 v62, 0xbfb8aa3b, v62
	v_rcp_f32_e32 v65, v65
	v_exp_f32_e32 v66, v66
	v_exp_f32_e32 v62, v62
	v_mul_f32_e32 v63, 0xbfb8aa3b, v63
	v_exp_f32_e32 v63, v63
	v_lshlrev_b32_e32 v70, 16, v139
	v_and_b32_e32 v71, 0xffff0000, v139
	v_lshlrev_b32_e32 v72, 16, v140
	v_mul_f32_e32 v61, v61, v70
	v_mul_f32_e32 v64, v64, v71
	v_pk_add_f32 v[56:57], v[56:57], v[96:97]
	v_cvt_pk_bf16_f32 v61, v61, v64
	v_mul_f32_e32 v64, v65, v72
	v_add_f32_e32 v65, 1.0, v66
	v_add_f32_e32 v62, 1.0, v62
	v_mul_f32_e32 v56, 0xbfb8aa3b, v56
	v_rcp_f32_e32 v65, v65
	v_rcp_f32_e32 v66, v62
	v_add_f32_e32 v62, 1.0, v63
	v_exp_f32_e32 v56, v56
	v_mul_f32_e32 v57, 0xbfb8aa3b, v57
	v_rcp_f32_e32 v63, v62
	v_exp_f32_e32 v57, v57
	v_and_b32_e32 v73, 0xffff0000, v140
	v_lshlrev_b32_e32 v74, 16, v141
	v_and_b32_e32 v75, 0xffff0000, v141
	v_mul_f32_e32 v62, v65, v73
	v_add_f32_e32 v56, 1.0, v56
	v_cvt_pk_bf16_f32 v62, v64, v62
	v_mul_f32_e32 v64, v66, v74
	v_mul_f32_e32 v63, v63, v75
	v_rcp_f32_e32 v56, v56
	v_add_f32_e32 v57, 1.0, v57
	v_cvt_pk_bf16_f32 v63, v64, v63
	v_lshl_add_u64 v[64:65], s[50:51], 0, v[124:125]
	v_rcp_f32_e32 v57, v57
	v_lshl_add_u64 v[64:65], v[64:65], 0, v[198:199]
	global_store_dwordx4 v[64:65], v[60:63], off
	v_pk_add_f32 v[58:59], v[58:59], v[98:99]
	v_pk_add_f32 v[54:55], v[54:55], v[94:95]
	v_pk_add_f32 v[60:61], v[52:53], v[92:93]
	s_waitcnt vmcnt(8)
	v_lshlrev_b32_e32 v52, 16, v116
	v_and_b32_e32 v53, 0xffff0000, v116
	v_mul_f32_e32 v58, 0xbfb8aa3b, v58
	v_mul_f32_e32 v52, v56, v52
	v_mul_f32_e32 v56, 0xbfb8aa3b, v59
	v_exp_f32_e32 v58, v58
	v_mul_f32_e32 v53, v57, v53
	v_exp_f32_e32 v56, v56
	v_mul_f32_e32 v57, 0xbfb8aa3b, v60
	v_exp_f32_e32 v57, v57
	v_cvt_pk_bf16_f32 v52, v52, v53
	v_add_f32_e32 v53, 1.0, v58
	v_add_f32_e32 v56, 1.0, v56
	v_mul_f32_e32 v54, 0xbfb8aa3b, v54
	v_rcp_f32_e32 v53, v53
	v_rcp_f32_e32 v56, v56
	v_add_f32_e32 v57, 1.0, v57
	v_mul_f32_e32 v58, 0xbfb8aa3b, v61
	v_exp_f32_e32 v54, v54
	v_mul_f32_e32 v55, 0xbfb8aa3b, v55
	v_rcp_f32_e32 v57, v57
	v_exp_f32_e32 v58, v58
	v_exp_f32_e32 v55, v55
	v_pk_add_f32 v[48:49], v[48:49], v[112:113]
	v_lshlrev_b32_e32 v62, 16, v117
	v_mul_f32_e32 v48, 0xbfb8aa3b, v48
	v_and_b32_e32 v63, 0xffff0000, v117
	v_exp_f32_e32 v48, v48
	v_mul_f32_e32 v49, 0xbfb8aa3b, v49
	v_lshlrev_b32_e32 v66, 16, v118
	v_mul_f32_e32 v53, v53, v62
	v_mul_f32_e32 v56, v56, v63
	v_add_f32_e32 v54, 1.0, v54
	v_exp_f32_e32 v49, v49
	v_cvt_pk_bf16_f32 v53, v53, v56
	v_mul_f32_e32 v56, v57, v66
	v_add_f32_e32 v57, 1.0, v58
	v_rcp_f32_e32 v58, v54
	v_add_f32_e32 v54, 1.0, v55
	v_rcp_f32_e32 v57, v57
	v_rcp_f32_e32 v55, v54
	v_add_f32_e32 v48, 1.0, v48
	v_rcp_f32_e32 v48, v48
	v_add_f32_e32 v49, 1.0, v49
	v_and_b32_e32 v67, 0xffff0000, v118
	v_and_b32_e32 v69, 0xffff0000, v119
	v_rcp_f32_e32 v49, v49
	v_lshlrev_b32_e32 v68, 16, v119
	v_mul_f32_e32 v54, v57, v67
	v_mul_f32_e32 v55, v55, v69
	v_cvt_pk_bf16_f32 v54, v56, v54
	v_mul_f32_e32 v56, v58, v68
	v_cvt_pk_bf16_f32 v55, v56, v55
	global_store_dwordx4 v[64:65], v[52:55], off offset:256
	v_pk_add_f32 v[50:51], v[50:51], v[114:115]
	v_pk_add_f32 v[46:47], v[46:47], v[110:111]
	v_pk_add_f32 v[52:53], v[44:45], v[108:109]
	s_waitcnt vmcnt(8)
	v_lshlrev_b32_e32 v44, 16, v104
	v_and_b32_e32 v45, 0xffff0000, v104
	v_mul_f32_e32 v50, 0xbfb8aa3b, v50
	v_mul_f32_e32 v44, v48, v44
	v_mul_f32_e32 v48, 0xbfb8aa3b, v51
	v_exp_f32_e32 v50, v50
	v_mul_f32_e32 v45, v49, v45
	v_exp_f32_e32 v48, v48
	v_mul_f32_e32 v49, 0xbfb8aa3b, v52
	v_exp_f32_e32 v49, v49
	v_cvt_pk_bf16_f32 v44, v44, v45
	v_add_f32_e32 v45, 1.0, v50
	v_add_f32_e32 v48, 1.0, v48
	v_rcp_f32_e32 v45, v45
	v_rcp_f32_e32 v48, v48
	v_add_f32_e32 v49, 1.0, v49
	v_mul_f32_e32 v50, 0xbfb8aa3b, v53
	v_mul_f32_e32 v46, 0xbfb8aa3b, v46
	v_rcp_f32_e32 v49, v49
	v_exp_f32_e32 v50, v50
	v_exp_f32_e32 v46, v46
	v_mul_f32_e32 v47, 0xbfb8aa3b, v47
	v_exp_f32_e32 v47, v47
	v_lshlrev_b32_e32 v54, 16, v105
	v_and_b32_e32 v55, 0xffff0000, v105
	v_lshlrev_b32_e32 v56, 16, v106
	v_mul_f32_e32 v45, v45, v54
	v_mul_f32_e32 v48, v48, v55
	v_pk_add_f32 v[40:41], v[40:41], v[96:97]
	v_cvt_pk_bf16_f32 v45, v45, v48
	v_mul_f32_e32 v48, v49, v56
	v_add_f32_e32 v49, 1.0, v50
	v_add_f32_e32 v46, 1.0, v46
	v_mul_f32_e32 v40, 0xbfb8aa3b, v40
	v_rcp_f32_e32 v49, v49
	v_rcp_f32_e32 v50, v46
	v_add_f32_e32 v46, 1.0, v47
	v_exp_f32_e32 v40, v40
	v_mul_f32_e32 v41, 0xbfb8aa3b, v41
	v_rcp_f32_e32 v47, v46
	v_exp_f32_e32 v41, v41
	v_and_b32_e32 v57, 0xffff0000, v106
	v_lshlrev_b32_e32 v58, 16, v107
	v_and_b32_e32 v59, 0xffff0000, v107
	v_mul_f32_e32 v46, v49, v57
	v_add_f32_e32 v40, 1.0, v40
	v_cvt_pk_bf16_f32 v46, v48, v46
	v_mul_f32_e32 v48, v50, v58
	v_mul_f32_e32 v47, v47, v59
	v_rcp_f32_e32 v40, v40
	v_add_f32_e32 v41, 1.0, v41
	v_cvt_pk_bf16_f32 v47, v48, v47
	v_lshl_add_u64 v[48:49], s[50:51], 0, v[122:123]
	v_rcp_f32_e32 v41, v41
	v_lshl_add_u64 v[48:49], v[48:49], 0, v[198:199]
	global_store_dwordx4 v[48:49], v[44:47], off
	v_pk_add_f32 v[42:43], v[42:43], v[98:99]
	v_pk_add_f32 v[38:39], v[38:39], v[94:95]
	v_pk_add_f32 v[44:45], v[36:37], v[92:93]
	s_waitcnt vmcnt(8)
; #define PG8_BAR __builtin_amdgcn_s_barrier()
; __device__ __forceinline__ unsigned pk2(float lo, float hi) { return pg8::cvt_pk_bf16(lo, hi); }
; __device__ __forceinline__ float sigm(float x) { return __builtin_amdgcn_rcpf(1.f + __builtin_amdgcn_exp2f(-LOG2E * x)); }
; __device__ __forceinline__ void unpack8(const u32x4 w, float (&f)[8]) { f[0] = bflo(w.x); f[1] = bfhi(w.x); f[2] = bflo(w.y); f[3] = bfhi(w.y); f[4] = bflo(w.z); f[5] = bfhi(w.z); f[6] = bflo(w.w); f[7] = bfhi(w.w); }
; template <class Epi, class Sched, bool ALIGN_EPI = false, bool SP2 = false>
; __device__ __forceinline__ void gemm_phase(PG8_LAS unsigned char* lds, const Gemm g, const Sched& S, const Epi& E) {
;     ...
;         if constexpr (ALIGN_EPI) { if (wr == 0) PG8_BAR; }
;         if constexpr (!Epi::AFTER_DRAIN) { E(acc, cur, wr, wc, fr, fq); S.done(cur); }
;         if (!has_next) break;
; #pragma unroll
;         for (int a = 0; a < 2; ++a)
; #pragma unroll
;             for (int b = 0; b < 2; ++b)
; #pragma unroll
;                 for (int m = 0; m < 4; ++m)
; #pragma unroll
;                     for (int n = 0; n < 2; ++n) acc[a][b][m][n] = (f32x4){0.f, 0.f, 0.f, 0.f};
;         cur = nxt; cA = nA; cB = nB; ++ui;
;         if constexpr (ALIGN_EPI) { if (wr == 1) PG8_BAR; }
;     __device__ __forceinline__ void operator()(const f32x4 (&acc)[2][2][4][2], const Unit& u, int wr, int wc, int fr, int fq) const {
;     ...
;             for (int m = 0; m < 4; ++m) { const size_t off = (size_t)(row0 + ai * 128 + m * 16) * 512 + col0;
; #pragma unroll
;                 for (int bj = 0; bj < 2; ++bj) { const f32x4 v0 = acc[ai][bj][m][0] + bv[bj][0], v1 = acc[ai][bj][m][1] + bv[bj][1];
;                     float y[8]; unpack8(yraw[m][bj], y);
;                     u32x4 w; w.x = pk2(y[0] * sigm(v0[0]), y[1] * sigm(v0[1])); w.y = pk2(y[2] * sigm(v0[2]), y[3] * sigm(v0[3]));
;                     w.z = pk2(y[4] * sigm(v1[0]), y[5] * sigm(v1[1])); w.w = pk2(y[6] * sigm(v1[2]), y[7] * sigm(v1[3]));
;                     *(u32x4*)(O + off + bj * 128) = w; } } }
	v_lshlrev_b32_e32 v36, 16, v100
	v_and_b32_e32 v37, 0xffff0000, v100
	v_mul_f32_e32 v42, 0xbfb8aa3b, v42
	v_mul_f32_e32 v36, v40, v36
	v_mul_f32_e32 v40, 0xbfb8aa3b, v43
	v_exp_f32_e32 v42, v42
	v_mul_f32_e32 v37, v41, v37
	v_exp_f32_e32 v40, v40
	v_mul_f32_e32 v41, 0xbfb8aa3b, v44
	v_exp_f32_e32 v41, v41
	v_cvt_pk_bf16_f32 v36, v36, v37
	v_add_f32_e32 v37, 1.0, v42
	v_add_f32_e32 v40, 1.0, v40
	v_mul_f32_e32 v38, 0xbfb8aa3b, v38
	v_rcp_f32_e32 v37, v37
	v_rcp_f32_e32 v40, v40
	v_add_f32_e32 v41, 1.0, v41
	v_mul_f32_e32 v42, 0xbfb8aa3b, v45
	v_exp_f32_e32 v38, v38
	v_mul_f32_e32 v39, 0xbfb8aa3b, v39
	v_rcp_f32_e32 v41, v41
	v_exp_f32_e32 v42, v42
	v_exp_f32_e32 v39, v39
	v_pk_add_f32 v[32:33], v[32:33], v[112:113]
	v_lshlrev_b32_e32 v46, 16, v101
	v_mul_f32_e32 v32, 0xbfb8aa3b, v32
	v_and_b32_e32 v47, 0xffff0000, v101
	v_exp_f32_e32 v32, v32
	v_mul_f32_e32 v33, 0xbfb8aa3b, v33
	v_lshlrev_b32_e32 v50, 16, v102
	v_mul_f32_e32 v37, v37, v46
	v_mul_f32_e32 v40, v40, v47
	v_add_f32_e32 v38, 1.0, v38
	v_exp_f32_e32 v33, v33
	v_cvt_pk_bf16_f32 v37, v37, v40
	v_mul_f32_e32 v40, v41, v50
	v_add_f32_e32 v41, 1.0, v42
	v_rcp_f32_e32 v42, v38
	v_add_f32_e32 v38, 1.0, v39
	v_rcp_f32_e32 v41, v41
	v_rcp_f32_e32 v39, v38
	v_add_f32_e32 v32, 1.0, v32
	v_rcp_f32_e32 v32, v32
	v_add_f32_e32 v33, 1.0, v33
	v_and_b32_e32 v51, 0xffff0000, v102
	v_and_b32_e32 v53, 0xffff0000, v103
	v_rcp_f32_e32 v33, v33
	v_lshlrev_b32_e32 v52, 16, v103
	v_mul_f32_e32 v38, v41, v51
	v_mul_f32_e32 v39, v39, v53
	v_cvt_pk_bf16_f32 v38, v40, v38
	v_mul_f32_e32 v40, v42, v52
	v_cvt_pk_bf16_f32 v39, v40, v39
	global_store_dwordx4 v[48:49], v[36:39], off offset:256
	v_pk_add_f32 v[34:35], v[34:35], v[114:115]
	v_pk_add_f32 v[30:31], v[30:31], v[110:111]
	v_pk_add_f32 v[36:37], v[28:29], v[108:109]
	s_waitcnt vmcnt(8)
	v_lshlrev_b32_e32 v28, 16, v88
	v_and_b32_e32 v29, 0xffff0000, v88
	v_mul_f32_e32 v34, 0xbfb8aa3b, v34
	v_mul_f32_e32 v28, v32, v28
	v_mul_f32_e32 v32, 0xbfb8aa3b, v35
	v_exp_f32_e32 v34, v34
	v_mul_f32_e32 v29, v33, v29
	v_exp_f32_e32 v32, v32
	v_mul_f32_e32 v33, 0xbfb8aa3b, v36
	v_exp_f32_e32 v33, v33
	v_cvt_pk_bf16_f32 v28, v28, v29
	v_add_f32_e32 v29, 1.0, v34
	v_add_f32_e32 v32, 1.0, v32
	v_rcp_f32_e32 v29, v29
	v_rcp_f32_e32 v32, v32
	v_add_f32_e32 v33, 1.0, v33
	v_mul_f32_e32 v34, 0xbfb8aa3b, v37
	v_mul_f32_e32 v30, 0xbfb8aa3b, v30
	v_rcp_f32_e32 v33, v33
	v_exp_f32_e32 v34, v34
	v_exp_f32_e32 v30, v30
	v_mul_f32_e32 v31, 0xbfb8aa3b, v31
	v_exp_f32_e32 v31, v31
	v_lshlrev_b32_e32 v38, 16, v89
	v_and_b32_e32 v39, 0xffff0000, v89
	v_lshlrev_b32_e32 v40, 16, v90
	v_mul_f32_e32 v29, v29, v38
	v_mul_f32_e32 v32, v32, v39
	v_pk_add_f32 v[24:25], v[24:25], v[96:97]
	v_cvt_pk_bf16_f32 v29, v29, v32
	v_mul_f32_e32 v32, v33, v40
	v_add_f32_e32 v33, 1.0, v34
	v_add_f32_e32 v30, 1.0, v30
	v_mul_f32_e32 v24, 0xbfb8aa3b, v24
	v_rcp_f32_e32 v33, v33
	v_rcp_f32_e32 v34, v30
	v_add_f32_e32 v30, 1.0, v31
	v_exp_f32_e32 v24, v24
	v_mul_f32_e32 v25, 0xbfb8aa3b, v25
	v_rcp_f32_e32 v31, v30
	v_exp_f32_e32 v25, v25
	v_and_b32_e32 v41, 0xffff0000, v90
	v_lshlrev_b32_e32 v42, 16, v91
	v_and_b32_e32 v43, 0xffff0000, v91
	v_mul_f32_e32 v30, v33, v41
	v_add_f32_e32 v24, 1.0, v24
	v_cvt_pk_bf16_f32 v30, v32, v30
	v_mul_f32_e32 v32, v34, v42
	v_mul_f32_e32 v31, v31, v43
	v_rcp_f32_e32 v24, v24
	v_add_f32_e32 v25, 1.0, v25
	v_cvt_pk_bf16_f32 v31, v32, v31
	v_lshl_add_u64 v[32:33], s[50:51], 0, v[120:121]
	v_rcp_f32_e32 v25, v25
	v_lshl_add_u64 v[32:33], v[32:33], 0, v[198:199]
	global_store_dwordx4 v[32:33], v[28:31], off
	v_pk_add_f32 v[26:27], v[26:27], v[98:99]
	v_pk_add_f32 v[22:23], v[22:23], v[94:95]
	v_pk_add_f32 v[28:29], v[20:21], v[92:93]
	s_waitcnt vmcnt(8)
	v_lshlrev_b32_e32 v20, 16, v84
	v_and_b32_e32 v21, 0xffff0000, v84
	v_mul_f32_e32 v26, 0xbfb8aa3b, v26
	v_mul_f32_e32 v20, v24, v20
	v_mul_f32_e32 v24, 0xbfb8aa3b, v27
	v_exp_f32_e32 v26, v26
	v_mul_f32_e32 v21, v25, v21
	v_exp_f32_e32 v24, v24
	v_mul_f32_e32 v25, 0xbfb8aa3b, v28
	v_exp_f32_e32 v25, v25
	v_cvt_pk_bf16_f32 v20, v20, v21
	v_add_f32_e32 v21, 1.0, v26
	v_add_f32_e32 v24, 1.0, v24
	v_mul_f32_e32 v22, 0xbfb8aa3b, v22
	v_rcp_f32_e32 v21, v21
	v_rcp_f32_e32 v24, v24
	v_add_f32_e32 v25, 1.0, v25
	v_mul_f32_e32 v26, 0xbfb8aa3b, v29
	v_exp_f32_e32 v22, v22
	v_mul_f32_e32 v23, 0xbfb8aa3b, v23
	v_rcp_f32_e32 v25, v25
	v_exp_f32_e32 v26, v26
	v_exp_f32_e32 v23, v23
	v_lshlrev_b32_e32 v30, 16, v85
	v_and_b32_e32 v31, 0xffff0000, v85
	v_lshlrev_b32_e32 v34, 16, v86
	v_mul_f32_e32 v21, v21, v30
	v_mul_f32_e32 v24, v24, v31
	v_add_f32_e32 v22, 1.0, v22
	v_cvt_pk_bf16_f32 v21, v21, v24
	v_mul_f32_e32 v24, v25, v34
	v_add_f32_e32 v25, 1.0, v26
	v_rcp_f32_e32 v26, v22
	v_add_f32_e32 v22, 1.0, v23
	v_rcp_f32_e32 v25, v25
	v_rcp_f32_e32 v23, v22
	v_and_b32_e32 v35, 0xffff0000, v86
	v_and_b32_e32 v37, 0xffff0000, v87
	v_lshlrev_b32_e32 v36, 16, v87
	v_mul_f32_e32 v22, v25, v35
	v_mul_f32_e32 v23, v23, v37
	s_andn2_b64 vcc, exec, s[6:7]
	s_mov_b64 s[0:1], -1
	v_cvt_pk_bf16_f32 v22, v24, v22
	v_mul_f32_e32 v24, v26, v36
	v_cvt_pk_bf16_f32 v23, v24, v23
	global_store_dwordx4 v[32:33], v[20:23], off offset:256
	s_cbranch_vccnz .LBB0_551
	s_andn2_b64 vcc, exec, s[10:11]
	s_cbranch_vccnz .LBB0_550
	s_barrier
	s_branch .LBB0_550

; __device__ __forceinline__ unsigned pk2(float lo, float hi) { return pg8::cvt_pk_bf16(lo, hi); }
; __device__ __forceinline__ void unpack8(const u32x4 w, float (&f)[8]) { f[0] = bflo(w.x); f[1] = bfhi(w.x); f[2] = bflo(w.y); f[3] = bfhi(w.y); f[4] = bflo(w.z); f[5] = bfhi(w.z); f[6] = bflo(w.w); f[7] = bfhi(w.w); }
;     __device__ __forceinline__ void operator()(const f32x4 (&acc)[2][2][4][2], const Unit& u, int wr, int wc, int fr, int fq) const {
;         const int row0 = u.pm * 256 + wr * 64 + fr, col0 = u.pn * 256 + wc * 32 + 8 * fq;
; #pragma unroll
;         for (int ai = 0; ai < 2; ++ai) {
;             u32x4 graw[4][2], praw[4][2];
; #pragma unroll
;             for (int m = 0; m < 4; ++m)
; #pragma unroll
;                 for (int bj = 0; bj < 2; ++bj) { const int row = row0 + ai * 128 + m * 16; graw[m][bj] = *(const u32x4*)(Zg + (size_t)row * INC + col0 + bj * 128);
;                     if (SECOND) praw[m][bj] = *(const u32x4*)(O + (size_t)row * DM + col0 + bj * 128); }
;             __builtin_amdgcn_sched_barrier(0);
; #pragma unroll
;             for (int m = 0; m < 4; ++m) { const int row = row0 + ai * 128 + m * 16;
; #pragma unroll
;                 for (int bj = 0; bj < 2; ++bj) { const f32x4 a0 = acc[ai][bj][m][0], a1 = acc[ai][bj][m][1];
;                     float g[8]; unpack8(graw[m][bj], g);
;                     float v[8] = {g[0] * a0[0], g[1] * a0[1], g[2] * a0[2], g[3] * a0[3], g[4] * a1[0], g[5] * a1[1], g[6] * a1[2], g[7] * a1[3]};
;                     bf16_t* op = O + (size_t)row * DM + col0 + bj * 128;
;                     if (SECOND) { float p[8]; unpack8(praw[m][bj], p);
; #pragma unroll
;                         for (int k = 0; k < 8; ++k) v[k] += p[k]; }
;                     u32x4 w; w.x = pk2(v[0], v[1]); w.y = pk2(v[2], v[3]); w.z = pk2(v[4], v[5]); w.w = pk2(v[6], v[7]);
;                     *(u32x4*)op = w; } } }
.LBB0_679:
	v_lshl_or_b32 v156, s28, 8, v164
	v_ashrrev_i32_e32 v157, 31, v156
	v_readlane_b32 s0, v253, 58
	v_lshl_add_u32 v158, s29, 8, v162
	v_lshlrev_b64 v[156:157], 1, v[156:157]
	v_readlane_b32 s1, v253, 59
	v_or_b32_e32 v182, 16, v158
	v_or_b32_e32 v206, 32, v158
	v_lshl_add_u64 v[160:161], s[0:1], 0, v[156:157]
	v_or_b32_e32 v208, 48, v158
	v_mad_i64_i32 v[170:171], s[0:1], v158, s87, v[160:161]
	v_mad_i64_i32 v[178:179], s[0:1], v182, s87, v[160:161]
	v_mad_i64_i32 v[194:195], s[0:1], v206, s87, v[160:161]
	v_mad_i64_i32 v[202:203], s[0:1], v208, s87, v[160:161]
	global_load_dwordx4 v[166:169], v[170:171], off
	s_nop 0
	global_load_dwordx4 v[170:173], v[170:171], off offset:256
	s_nop 0
	global_load_dwordx4 v[174:177], v[178:179], off
	s_nop 0
	global_load_dwordx4 v[178:181], v[178:179], off offset:256
	s_nop 0
	global_load_dwordx4 v[190:193], v[194:195], off
	s_nop 0
	global_load_dwordx4 v[194:197], v[194:195], off offset:256
	s_nop 0
	global_load_dwordx4 v[198:201], v[202:203], off
	s_nop 0
	global_load_dwordx4 v[202:205], v[202:203], off offset:256
	s_cmp_lg_u64 s[6:7], 0
	s_cbranch_scc1 .Lskpf_g3a
	s_and_b32 s98, s2, 7
	s_lshl_b32 s98, s98, 16
	s_add_u32 s98, s98, 0x6a00000
	s_lshr_b32 s99, s2, 3
	s_and_b32 s99, s99, 31
	s_lshl_b32 s99, s99, 11
	s_add_u32 s98, s98, s99
	s_add_u32 s98, s70, s98
	s_addc_u32 s99, s71, 0
	v_and_b32_e32 v224, 15, v184
	v_lshlrev_b32_e32 v224, 7, v224
	v_mov_b32_e32 v225, 0
	v_lshl_add_u64 v[224:225], s[98:99], 0, v[224:225]
	global_load_dword v226, v[224:225], off
.Lskpf_g3a:
	v_ashrrev_i32_e32 v159, 31, v158
	v_ashrrev_i32_e32 v183, 31, v182
	v_ashrrev_i32_e32 v207, 31, v206
	v_ashrrev_i32_e32 v209, 31, v208
	v_lshlrev_b64 v[220:221], 11, v[158:159]
	s_waitcnt vmcnt(0)
	v_lshlrev_b32_e32 v159, 16, v166
	v_and_b32_e32 v166, 0xffff0000, v166
	v_lshlrev_b32_e32 v186, 16, v167
	v_and_b32_e32 v167, 0xffff0000, v167
	v_lshlrev_b32_e32 v187, 16, v168
	v_and_b32_e32 v168, 0xffff0000, v168
	v_lshlrev_b32_e32 v210, 16, v169
	v_and_b32_e32 v169, 0xffff0000, v169
	v_mul_f32_e32 v166, v145, v166
	v_mul_f32_e32 v147, v147, v167
	v_mul_f32_e32 v167, v140, v187
	v_mul_f32_e32 v168, v141, v168
	v_mul_f32_e32 v143, v143, v169
	v_lshl_add_u64 v[140:141], s[68:69], 0, v[220:221]
	v_mul_f32_e32 v159, v144, v159
	v_mul_f32_e32 v146, v146, v186
	v_mul_f32_e32 v186, v142, v210
	v_lshl_add_u64 v[144:145], v[140:141], 0, v[156:157]
	v_cvt_pk_bf16_f32 v140, v159, v166
	v_cvt_pk_bf16_f32 v141, v146, v147
	v_cvt_pk_bf16_f32 v142, v167, v168
	v_cvt_pk_bf16_f32 v143, v186, v143
	v_and_b32_e32 v166, 0xffff0000, v173
	global_store_dwordx4 v[144:145], v[140:143], off
	v_lshlrev_b32_e32 v146, 16, v172
	v_and_b32_e32 v147, 0xffff0000, v172
	v_lshlrev_b32_e32 v140, 16, v170
	v_and_b32_e32 v141, 0xffff0000, v170
	v_lshlrev_b32_e32 v142, 16, v171
	v_and_b32_e32 v143, 0xffff0000, v171
	v_lshlrev_b32_e32 v159, 16, v173
	v_mul_f32_e32 v131, v131, v166
	v_mul_f32_e32 v136, v136, v140
	v_mul_f32_e32 v137, v137, v141
	v_mul_f32_e32 v138, v138, v142
	v_mul_f32_e32 v139, v139, v143
	v_mul_f32_e32 v140, v128, v146
	v_mul_f32_e32 v141, v129, v147
	v_mul_f32_e32 v142, v130, v159
	v_cvt_pk_bf16_f32 v128, v136, v137
	v_cvt_pk_bf16_f32 v129, v138, v139
	v_cvt_pk_bf16_f32 v130, v140, v141
	v_cvt_pk_bf16_f32 v131, v142, v131
	global_store_dwordx4 v[144:145], v[128:131], off offset:256
	v_lshlrev_b32_e32 v136, 16, v175
	v_and_b32_e32 v137, 0xffff0000, v175
	v_lshlrev_b64 v[128:129], 11, v[182:183]
	v_lshlrev_b32_e32 v130, 16, v174
	v_and_b32_e32 v131, 0xffff0000, v174
	v_lshlrev_b32_e32 v138, 16, v176
	v_and_b32_e32 v139, 0xffff0000, v176
	v_and_b32_e32 v141, 0xffff0000, v177
	v_lshlrev_b32_e32 v140, 16, v177
	v_mul_f32_e32 v130, v132, v130
	v_mul_f32_e32 v131, v133, v131
	v_mul_f32_e32 v132, v134, v136
	v_mul_f32_e32 v133, v135, v137
	v_mul_f32_e32 v134, v124, v138
	v_mul_f32_e32 v135, v125, v139
	v_mul_f32_e32 v127, v127, v141
	v_lshl_add_u64 v[124:125], s[68:69], 0, v[128:129]
	v_mul_f32_e32 v136, v126, v140
	v_lshl_add_u64 v[128:129], v[124:125], 0, v[156:157]
	v_cvt_pk_bf16_f32 v124, v130, v131
	v_cvt_pk_bf16_f32 v125, v132, v133
	v_cvt_pk_bf16_f32 v126, v134, v135
	v_cvt_pk_bf16_f32 v127, v136, v127
	v_and_b32_e32 v133, 0xffff0000, v181
	global_store_dwordx4 v[128:129], v[124:127], off
	v_lshlrev_b32_e32 v130, 16, v180
	v_and_b32_e32 v131, 0xffff0000, v180
	v_lshlrev_b32_e32 v124, 16, v178
	v_and_b32_e32 v125, 0xffff0000, v178
	v_lshlrev_b32_e32 v126, 16, v179
	v_and_b32_e32 v127, 0xffff0000, v179
	v_lshlrev_b32_e32 v132, 16, v181
	v_mul_f32_e32 v115, v115, v133
	v_mul_f32_e32 v120, v120, v124
	v_mul_f32_e32 v121, v121, v125
	v_mul_f32_e32 v122, v122, v126
	v_mul_f32_e32 v123, v123, v127
	v_mul_f32_e32 v124, v112, v130
	v_mul_f32_e32 v125, v113, v131
	v_mul_f32_e32 v126, v114, v132
	v_cvt_pk_bf16_f32 v112, v120, v121
	v_cvt_pk_bf16_f32 v113, v122, v123
	v_cvt_pk_bf16_f32 v114, v124, v125
	v_cvt_pk_bf16_f32 v115, v126, v115
	global_store_dwordx4 v[128:129], v[112:115], off offset:256
	v_lshlrev_b32_e32 v120, 16, v191
	v_and_b32_e32 v121, 0xffff0000, v191
	v_lshlrev_b64 v[112:113], 11, v[206:207]
	v_lshlrev_b32_e32 v114, 16, v190
	v_and_b32_e32 v115, 0xffff0000, v190
	v_lshlrev_b32_e32 v122, 16, v192
	v_and_b32_e32 v123, 0xffff0000, v192
	v_and_b32_e32 v125, 0xffff0000, v193
	v_lshlrev_b32_e32 v124, 16, v193
	v_mul_f32_e32 v114, v116, v114
	v_mul_f32_e32 v115, v117, v115
	v_mul_f32_e32 v116, v118, v120
	v_mul_f32_e32 v117, v119, v121
	v_mul_f32_e32 v118, v108, v122
	v_mul_f32_e32 v119, v109, v123
	v_mul_f32_e32 v111, v111, v125
	v_lshl_add_u64 v[108:109], s[68:69], 0, v[112:113]
	v_mul_f32_e32 v120, v110, v124
	v_lshl_add_u64 v[112:113], v[108:109], 0, v[156:157]
; __device__ __forceinline__ unsigned pk2(float lo, float hi) { return pg8::cvt_pk_bf16(lo, hi); }
; __device__ __forceinline__ void unpack8(const u32x4 w, float (&f)[8]) { f[0] = bflo(w.x); f[1] = bfhi(w.x); f[2] = bflo(w.y); f[3] = bfhi(w.y); f[4] = bflo(w.z); f[5] = bfhi(w.z); f[6] = bflo(w.w); f[7] = bfhi(w.w); }
;     __device__ __forceinline__ void operator()(const f32x4 (&acc)[2][2][4][2], const Unit& u, int wr, int wc, int fr, int fq) const {
;         const int row0 = u.pm * 256 + wr * 64 + fr, col0 = u.pn * 256 + wc * 32 + 8 * fq;
; #pragma unroll
;         for (int ai = 0; ai < 2; ++ai) {
;             u32x4 graw[4][2], praw[4][2];
; #pragma unroll
;             for (int m = 0; m < 4; ++m)
; #pragma unroll
;                 for (int bj = 0; bj < 2; ++bj) { const int row = row0 + ai * 128 + m * 16; graw[m][bj] = *(const u32x4*)(Zg + (size_t)row * INC + col0 + bj * 128);
;                     if (SECOND) praw[m][bj] = *(const u32x4*)(O + (size_t)row * DM + col0 + bj * 128); }
;             __builtin_amdgcn_sched_barrier(0);
; #pragma unroll
;             for (int m = 0; m < 4; ++m) { const int row = row0 + ai * 128 + m * 16;
; #pragma unroll
;                 for (int bj = 0; bj < 2; ++bj) { const f32x4 a0 = acc[ai][bj][m][0], a1 = acc[ai][bj][m][1];
;                     float g[8]; unpack8(graw[m][bj], g);
;                     float v[8] = {g[0] * a0[0], g[1] * a0[1], g[2] * a0[2], g[3] * a0[3], g[4] * a1[0], g[5] * a1[1], g[6] * a1[2], g[7] * a1[3]};
;                     bf16_t* op = O + (size_t)row * DM + col0 + bj * 128;
;                     if (SECOND) { float p[8]; unpack8(praw[m][bj], p);
; #pragma unroll
;                         for (int k = 0; k < 8; ++k) v[k] += p[k]; }
;                     u32x4 w; w.x = pk2(v[0], v[1]); w.y = pk2(v[2], v[3]); w.z = pk2(v[4], v[5]); w.w = pk2(v[6], v[7]);
;                     *(u32x4*)op = w; } } }
	v_cvt_pk_bf16_f32 v108, v114, v115
	v_cvt_pk_bf16_f32 v109, v116, v117
	v_cvt_pk_bf16_f32 v110, v118, v119
	v_cvt_pk_bf16_f32 v111, v120, v111
	v_and_b32_e32 v117, 0xffff0000, v197
	global_store_dwordx4 v[112:113], v[108:111], off
	v_lshlrev_b32_e32 v114, 16, v196
	v_and_b32_e32 v115, 0xffff0000, v196
	v_lshlrev_b32_e32 v108, 16, v194
	v_and_b32_e32 v109, 0xffff0000, v194
	v_lshlrev_b32_e32 v110, 16, v195
	v_and_b32_e32 v111, 0xffff0000, v195
	v_lshlrev_b32_e32 v116, 16, v197
	v_mul_f32_e32 v99, v99, v117
	v_mul_f32_e32 v104, v104, v108
	v_mul_f32_e32 v105, v105, v109
	v_mul_f32_e32 v106, v106, v110
	v_mul_f32_e32 v107, v107, v111
	v_mul_f32_e32 v108, v96, v114
	v_mul_f32_e32 v109, v97, v115
	v_mul_f32_e32 v110, v98, v116
	v_cvt_pk_bf16_f32 v96, v104, v105
	v_cvt_pk_bf16_f32 v97, v106, v107
	v_cvt_pk_bf16_f32 v98, v108, v109
	v_cvt_pk_bf16_f32 v99, v110, v99
	global_store_dwordx4 v[112:113], v[96:99], off offset:256
	v_lshlrev_b32_e32 v104, 16, v199
	v_and_b32_e32 v105, 0xffff0000, v199
	v_lshlrev_b64 v[96:97], 11, v[208:209]
	v_lshlrev_b32_e32 v98, 16, v198
	v_and_b32_e32 v99, 0xffff0000, v198
	v_lshlrev_b32_e32 v106, 16, v200
	v_and_b32_e32 v107, 0xffff0000, v200
	v_and_b32_e32 v109, 0xffff0000, v201
	v_mul_f32_e32 v98, v100, v98
	v_mul_f32_e32 v99, v101, v99
	v_mul_f32_e32 v100, v102, v104
	v_mul_f32_e32 v101, v103, v105
	v_mul_f32_e32 v102, v92, v106
	v_mul_f32_e32 v103, v93, v107
	v_lshl_add_u64 v[92:93], s[68:69], 0, v[96:97]
	v_lshlrev_b32_e32 v108, 16, v201
	v_mul_f32_e32 v95, v95, v109
	v_lshl_add_u64 v[96:97], v[92:93], 0, v[156:157]
	v_cvt_pk_bf16_f32 v92, v98, v99
	v_cvt_pk_bf16_f32 v93, v100, v101
	v_mul_f32_e32 v104, v94, v108
	v_cvt_pk_bf16_f32 v94, v102, v103
	v_cvt_pk_bf16_f32 v95, v104, v95
	global_store_dwordx4 v[96:97], v[92:95], off
	v_and_b32_e32 v101, 0xffff0000, v205
	v_lshlrev_b32_e32 v98, 16, v204
	v_lshlrev_b32_e32 v92, 16, v202
	v_and_b32_e32 v93, 0xffff0000, v202
	v_lshlrev_b32_e32 v94, 16, v203
	v_and_b32_e32 v95, 0xffff0000, v203
	v_and_b32_e32 v99, 0xffff0000, v204
	v_lshlrev_b32_e32 v100, 16, v205
	v_mul_f32_e32 v88, v88, v92
	v_mul_f32_e32 v89, v89, v93
	v_mul_f32_e32 v87, v87, v101
	v_add_u32_e32 v116, 0x80, v158
	v_add_u32_e32 v118, 0x90, v158
	v_add_u32_e32 v120, 0xa0, v158
	v_add_u32_e32 v122, 0xb0, v158
	v_mul_f32_e32 v90, v90, v94
	v_mul_f32_e32 v91, v91, v95
	v_mul_f32_e32 v92, v84, v98
	v_mul_f32_e32 v93, v85, v99
	v_mul_f32_e32 v94, v86, v100
	v_cvt_pk_bf16_f32 v84, v88, v89
	v_cvt_pk_bf16_f32 v85, v90, v91
	v_cvt_pk_bf16_f32 v86, v92, v93
	v_cvt_pk_bf16_f32 v87, v94, v87
	global_store_dwordx4 v[96:97], v[84:87], off offset:256
	v_mad_i64_i32 v[88:89], s[0:1], v116, s87, v[160:161]
	v_mad_i64_i32 v[96:97], s[0:1], v118, s87, v[160:161]
	v_mad_i64_i32 v[104:105], s[0:1], v120, s87, v[160:161]
	v_mad_i64_i32 v[112:113], s[0:1], v122, s87, v[160:161]
	global_load_dwordx4 v[84:87], v[88:89], off
	s_nop 0
	global_load_dwordx4 v[88:91], v[88:89], off offset:256
	s_nop 0
	global_load_dwordx4 v[92:95], v[96:97], off
	s_nop 0
	global_load_dwordx4 v[96:99], v[96:97], off offset:256
	s_nop 0
	global_load_dwordx4 v[100:103], v[104:105], off
	s_nop 0
	global_load_dwordx4 v[104:107], v[104:105], off offset:256
	s_nop 0
	global_load_dwordx4 v[108:111], v[112:113], off
	s_nop 0
	global_load_dwordx4 v[112:115], v[112:113], off offset:256
	v_ashrrev_i32_e32 v117, 31, v116
	v_ashrrev_i32_e32 v119, 31, v118
	v_ashrrev_i32_e32 v121, 31, v120
	v_ashrrev_i32_e32 v123, 31, v122
	v_lshlrev_b64 v[116:117], 11, v[116:117]
	s_waitcnt vmcnt(7)
	v_lshlrev_b32_e32 v125, 16, v85
	v_and_b32_e32 v85, 0xffff0000, v85
	v_lshlrev_b32_e32 v126, 16, v86
	v_and_b32_e32 v86, 0xffff0000, v86
	v_lshlrev_b32_e32 v127, 16, v87
	v_and_b32_e32 v87, 0xffff0000, v87
	v_lshlrev_b32_e32 v124, 16, v84
	v_and_b32_e32 v84, 0xffff0000, v84
	v_mul_f32_e32 v83, v83, v85
	v_mul_f32_e32 v85, v76, v126
	v_mul_f32_e32 v86, v77, v86
	v_mul_f32_e32 v79, v79, v87
	v_lshl_add_u64 v[76:77], s[68:69], 0, v[116:117]
	v_mul_f32_e32 v124, v80, v124
	v_mul_f32_e32 v84, v81, v84
	v_mul_f32_e32 v82, v82, v125
	v_mul_f32_e32 v125, v78, v127
	v_lshl_add_u64 v[80:81], v[76:77], 0, v[156:157]
	v_cvt_pk_bf16_f32 v76, v124, v84
	v_cvt_pk_bf16_f32 v77, v82, v83
	v_cvt_pk_bf16_f32 v78, v85, v86
	v_cvt_pk_bf16_f32 v79, v125, v79
	s_waitcnt vmcnt(6)
	v_and_b32_e32 v85, 0xffff0000, v91
	global_store_dwordx4 v[80:81], v[76:79], off
	v_lshlrev_b32_e32 v82, 16, v90
	v_and_b32_e32 v83, 0xffff0000, v90
	v_lshlrev_b32_e32 v76, 16, v88
	v_and_b32_e32 v77, 0xffff0000, v88
	v_lshlrev_b32_e32 v78, 16, v89
	v_and_b32_e32 v79, 0xffff0000, v89
	v_lshlrev_b32_e32 v84, 16, v91
	v_mul_f32_e32 v67, v67, v85
	v_mul_f32_e32 v72, v72, v76
	v_mul_f32_e32 v73, v73, v77
	v_mul_f32_e32 v74, v74, v78
	v_mul_f32_e32 v75, v75, v79
	v_mul_f32_e32 v76, v64, v82
	v_mul_f32_e32 v77, v65, v83
	v_mul_f32_e32 v78, v66, v84
	v_cvt_pk_bf16_f32 v64, v72, v73
	v_cvt_pk_bf16_f32 v65, v74, v75
	v_cvt_pk_bf16_f32 v66, v76, v77
	v_cvt_pk_bf16_f32 v67, v78, v67
	global_store_dwordx4 v[80:81], v[64:67], off offset:256
	s_waitcnt vmcnt(7)
; #define PG8_BAR __builtin_amdgcn_s_barrier()
; __device__ __forceinline__ unsigned pk2(float lo, float hi) { return pg8::cvt_pk_bf16(lo, hi); }
; __device__ __forceinline__ void unpack8(const u32x4 w, float (&f)[8]) { f[0] = bflo(w.x); f[1] = bfhi(w.x); f[2] = bflo(w.y); f[3] = bfhi(w.y); f[4] = bflo(w.z); f[5] = bfhi(w.z); f[6] = bflo(w.w); f[7] = bfhi(w.w); }
; template <class Epi, class Sched, bool ALIGN_EPI = false, bool SP2 = false>
; __device__ __forceinline__ void gemm_phase(PG8_LAS unsigned char* lds, const Gemm g, const Sched& S, const Epi& E) {
;     ...
;         if constexpr (ALIGN_EPI) { if (wr == 0) PG8_BAR; }
;         if constexpr (!Epi::AFTER_DRAIN) { E(acc, cur, wr, wc, fr, fq); S.done(cur); }
;         if (!has_next) break;
; #pragma unroll
;         for (int a = 0; a < 2; ++a)
; #pragma unroll
;             for (int b = 0; b < 2; ++b)
; #pragma unroll
;                 for (int m = 0; m < 4; ++m)
; #pragma unroll
;                     for (int n = 0; n < 2; ++n) acc[a][b][m][n] = (f32x4){0.f, 0.f, 0.f, 0.f};
;         cur = nxt; cA = nA; cB = nB; ++ui;
;         if constexpr (ALIGN_EPI) { if (wr == 1) PG8_BAR; }
;     __device__ __forceinline__ void operator()(const f32x4 (&acc)[2][2][4][2], const Unit& u, int wr, int wc, int fr, int fq) const {
;     ...
;             for (int m = 0; m < 4; ++m) { const int row = row0 + ai * 128 + m * 16;
; #pragma unroll
;                 for (int bj = 0; bj < 2; ++bj) { const f32x4 a0 = acc[ai][bj][m][0], a1 = acc[ai][bj][m][1];
;                     float g[8]; unpack8(graw[m][bj], g);
;                     float v[8] = {g[0] * a0[0], g[1] * a0[1], g[2] * a0[2], g[3] * a0[3], g[4] * a1[0], g[5] * a1[1], g[6] * a1[2], g[7] * a1[3]};
;                     bf16_t* op = O + (size_t)row * DM + col0 + bj * 128;
;                     if (SECOND) { float p[8]; unpack8(praw[m][bj], p);
; #pragma unroll
;                         for (int k = 0; k < 8; ++k) v[k] += p[k]; }
;                     u32x4 w; w.x = pk2(v[0], v[1]); w.y = pk2(v[2], v[3]); w.z = pk2(v[4], v[5]); w.w = pk2(v[6], v[7]);
;                     *(u32x4*)op = w; } } }
	v_lshlrev_b32_e32 v72, 16, v93
	v_and_b32_e32 v73, 0xffff0000, v93
	v_lshlrev_b64 v[64:65], 11, v[118:119]
	v_lshlrev_b32_e32 v66, 16, v92
	v_and_b32_e32 v67, 0xffff0000, v92
	v_lshlrev_b32_e32 v74, 16, v94
	v_and_b32_e32 v75, 0xffff0000, v94
	v_and_b32_e32 v77, 0xffff0000, v95
	v_lshlrev_b32_e32 v76, 16, v95
	v_mul_f32_e32 v66, v68, v66
	v_mul_f32_e32 v67, v69, v67
	v_mul_f32_e32 v68, v70, v72
	v_mul_f32_e32 v69, v71, v73
	v_mul_f32_e32 v70, v60, v74
	v_mul_f32_e32 v71, v61, v75
	v_mul_f32_e32 v63, v63, v77
	v_lshl_add_u64 v[60:61], s[68:69], 0, v[64:65]
	v_mul_f32_e32 v72, v62, v76
	v_lshl_add_u64 v[64:65], v[60:61], 0, v[156:157]
	v_cvt_pk_bf16_f32 v60, v66, v67
	v_cvt_pk_bf16_f32 v61, v68, v69
	v_cvt_pk_bf16_f32 v62, v70, v71
	v_cvt_pk_bf16_f32 v63, v72, v63
	s_waitcnt vmcnt(6)
	v_and_b32_e32 v69, 0xffff0000, v99
	global_store_dwordx4 v[64:65], v[60:63], off
	v_lshlrev_b32_e32 v66, 16, v98
	v_and_b32_e32 v67, 0xffff0000, v98
	v_lshlrev_b32_e32 v60, 16, v96
	v_and_b32_e32 v61, 0xffff0000, v96
	v_lshlrev_b32_e32 v62, 16, v97
	v_and_b32_e32 v63, 0xffff0000, v97
	v_lshlrev_b32_e32 v68, 16, v99
	v_mul_f32_e32 v51, v51, v69
	v_mul_f32_e32 v56, v56, v60
	v_mul_f32_e32 v57, v57, v61
	v_mul_f32_e32 v58, v58, v62
	v_mul_f32_e32 v59, v59, v63
	v_mul_f32_e32 v60, v48, v66
	v_mul_f32_e32 v61, v49, v67
	v_mul_f32_e32 v62, v50, v68
	v_cvt_pk_bf16_f32 v48, v56, v57
	v_cvt_pk_bf16_f32 v49, v58, v59
	v_cvt_pk_bf16_f32 v50, v60, v61
	v_cvt_pk_bf16_f32 v51, v62, v51
	global_store_dwordx4 v[64:65], v[48:51], off offset:256
	s_waitcnt vmcnt(7)
	v_lshlrev_b32_e32 v56, 16, v101
	v_and_b32_e32 v57, 0xffff0000, v101
	v_lshlrev_b64 v[48:49], 11, v[120:121]
	v_lshlrev_b32_e32 v50, 16, v100
	v_and_b32_e32 v51, 0xffff0000, v100
	v_lshlrev_b32_e32 v58, 16, v102
	v_and_b32_e32 v59, 0xffff0000, v102
	v_and_b32_e32 v61, 0xffff0000, v103
	v_lshlrev_b32_e32 v60, 16, v103
	v_mul_f32_e32 v50, v52, v50
	v_mul_f32_e32 v51, v53, v51
	v_mul_f32_e32 v52, v54, v56
	v_mul_f32_e32 v53, v55, v57
	v_mul_f32_e32 v54, v44, v58
	v_mul_f32_e32 v55, v45, v59
	v_mul_f32_e32 v47, v47, v61
	v_lshl_add_u64 v[44:45], s[68:69], 0, v[48:49]
	v_mul_f32_e32 v56, v46, v60
	v_lshl_add_u64 v[48:49], v[44:45], 0, v[156:157]
	v_cvt_pk_bf16_f32 v44, v50, v51
	v_cvt_pk_bf16_f32 v45, v52, v53
	v_cvt_pk_bf16_f32 v46, v54, v55
	v_cvt_pk_bf16_f32 v47, v56, v47
	s_waitcnt vmcnt(6)
	v_and_b32_e32 v53, 0xffff0000, v107
	global_store_dwordx4 v[48:49], v[44:47], off
	v_lshlrev_b32_e32 v50, 16, v106
	v_and_b32_e32 v51, 0xffff0000, v106
	v_lshlrev_b32_e32 v44, 16, v104
	v_and_b32_e32 v45, 0xffff0000, v104
	v_lshlrev_b32_e32 v46, 16, v105
	v_and_b32_e32 v47, 0xffff0000, v105
	v_lshlrev_b32_e32 v52, 16, v107
	v_mul_f32_e32 v35, v35, v53
	v_mul_f32_e32 v40, v40, v44
	v_mul_f32_e32 v41, v41, v45
	v_mul_f32_e32 v42, v42, v46
	v_mul_f32_e32 v43, v43, v47
	v_mul_f32_e32 v44, v32, v50
	v_mul_f32_e32 v45, v33, v51
	v_mul_f32_e32 v46, v34, v52
	v_cvt_pk_bf16_f32 v32, v40, v41
	v_cvt_pk_bf16_f32 v33, v42, v43
	v_cvt_pk_bf16_f32 v34, v44, v45
	v_cvt_pk_bf16_f32 v35, v46, v35
	global_store_dwordx4 v[48:49], v[32:35], off offset:256
	s_waitcnt vmcnt(7)
	v_lshlrev_b32_e32 v40, 16, v109
	v_and_b32_e32 v41, 0xffff0000, v109
	v_lshlrev_b64 v[32:33], 11, v[122:123]
	v_lshlrev_b32_e32 v34, 16, v108
	v_and_b32_e32 v35, 0xffff0000, v108
	v_lshlrev_b32_e32 v42, 16, v110
	v_and_b32_e32 v43, 0xffff0000, v110
	v_and_b32_e32 v45, 0xffff0000, v111
	v_lshlrev_b32_e32 v44, 16, v111
	v_mul_f32_e32 v34, v36, v34
	v_mul_f32_e32 v35, v37, v35
	v_mul_f32_e32 v36, v38, v40
	v_mul_f32_e32 v37, v39, v41
	v_mul_f32_e32 v38, v28, v42
	v_mul_f32_e32 v39, v29, v43
	v_mul_f32_e32 v31, v31, v45
	v_lshl_add_u64 v[28:29], s[68:69], 0, v[32:33]
	v_mul_f32_e32 v40, v30, v44
	v_lshl_add_u64 v[32:33], v[28:29], 0, v[156:157]
	v_cvt_pk_bf16_f32 v28, v34, v35
	v_cvt_pk_bf16_f32 v29, v36, v37
	v_cvt_pk_bf16_f32 v30, v38, v39
	v_cvt_pk_bf16_f32 v31, v40, v31
	s_waitcnt vmcnt(6)
	v_and_b32_e32 v37, 0xffff0000, v115
	global_store_dwordx4 v[32:33], v[28:31], off
	v_lshlrev_b32_e32 v34, 16, v114
	v_and_b32_e32 v35, 0xffff0000, v114
	v_lshlrev_b32_e32 v28, 16, v112
	v_and_b32_e32 v29, 0xffff0000, v112
	v_lshlrev_b32_e32 v30, 16, v113
	v_and_b32_e32 v31, 0xffff0000, v113
	v_lshlrev_b32_e32 v36, 16, v115
	v_mul_f32_e32 v23, v23, v37
	s_andn2_b64 vcc, exec, s[6:7]
	s_mov_b64 s[0:1], -1
	s_mov_b32 s35, 0x18000
	s_mov_b32 s72, 0xc000
	v_mul_f32_e32 v24, v24, v28
	v_mul_f32_e32 v25, v25, v29
	v_mul_f32_e32 v26, v26, v30
	v_mul_f32_e32 v27, v27, v31
	v_mul_f32_e32 v28, v20, v34
	v_mul_f32_e32 v29, v21, v35
	v_mul_f32_e32 v30, v22, v36
	v_cvt_pk_bf16_f32 v20, v24, v25
	v_cvt_pk_bf16_f32 v21, v26, v27
	v_cvt_pk_bf16_f32 v22, v28, v29
	v_cvt_pk_bf16_f32 v23, v30, v23
	global_store_dwordx4 v[32:33], v[20:23], off offset:256
	s_cbranch_vccnz .LBB0_668
	s_andn2_b64 vcc, exec, s[4:5]
	s_cbranch_vccnz .LBB0_667
	s_barrier
	s_branch .LBB0_667

;     __device__ __forceinline__ void operator()(const f32x4 (&acc)[2][2][4][2], const Unit& u, int wr, int wc, int fr, int fq) const {
;         const int row0 = u.pm * 256 + wr * 64 + fr, col0 = u.pn * 256 + wc * 32 + 8 * fq;
; #pragma unroll
;         for (int ai = 0; ai < 2; ++ai) {
;             u32x4 braw[4][2];
; #pragma unroll
;             for (int m = 0; m < 4; ++m)
; #pragma unroll
;                 for (int bj = 0; bj < 2; ++bj) braw[m][bj] = *(const u32x4*)(base + (size_t)(row0 + ai * 128 + m * 16) * DM + col0 + bj * 128);
.LBB0_777:
	v_lshl_or_b32 v180, s28, 8, v206
	v_lshl_add_u32 v182, s29, 8, v204
	v_ashrrev_i32_e32 v181, 31, v180
	v_lshlrev_b64 v[186:187], 1, v[180:181]
	v_ashrrev_i32_e32 v183, 31, v182
	v_or_b32_e32 v200, 16, v182
	v_lshl_add_u64 v[190:191], s[30:31], 0, v[186:187]
	v_lshlrev_b64 v[208:209], 11, v[182:183]
	v_ashrrev_i32_e32 v201, 31, v200
	v_or_b32_e32 v196, 32, v182
	v_lshl_add_u64 v[148:149], v[190:191], 0, v[208:209]
	v_lshlrev_b64 v[202:203], 11, v[200:201]
	v_ashrrev_i32_e32 v197, 31, v196
	v_or_b32_e32 v192, 48, v182
	global_load_dwordx4 v[220:223], v[148:149], off
	global_load_dwordx4 v[224:227], v[148:149], off offset:256
	v_lshl_add_u64 v[148:149], v[190:191], 0, v[202:203]
	v_lshlrev_b64 v[198:199], 11, v[196:197]
	v_ashrrev_i32_e32 v193, 31, v192
	global_load_dwordx4 v[168:171], v[148:149], off
	global_load_dwordx4 v[164:167], v[148:149], off offset:256
	v_lshl_add_u64 v[148:149], v[190:191], 0, v[198:199]
	v_lshlrev_b64 v[194:195], 11, v[192:193]
	global_load_dwordx4 v[160:163], v[148:149], off
	global_load_dwordx4 v[156:159], v[148:149], off offset:256
	v_lshl_add_u64 v[148:149], v[190:191], 0, v[194:195]
	global_load_dwordx4 v[152:155], v[148:149], off
	s_nop 0
	global_load_dwordx4 v[148:151], v[148:149], off offset:256
	s_cmp_lg_u64 s[10:11], 0
	s_cbranch_scc1 .Lskpf_g4
	s_and_b32 s98, s2, 7
	s_lshl_b32 s98, s98, 17
	s_add_u32 s98, s98, 0x2000000
	s_lshr_b32 s99, s2, 3
	s_and_b32 s99, s99, 31
	s_lshl_b32 s99, s99, 12
	s_add_u32 s98, s98, s99
	s_add_u32 s98, s68, s98
	s_addc_u32 s99, s69, 0
	v_and_b32_e32 v240, 31, v184
	v_lshlrev_b32_e32 v240, 7, v240
	v_mov_b32_e32 v241, 0
	v_lshl_add_u64 v[240:241], s[98:99], 0, v[240:241]
	global_load_dword v242, v[240:241], off

; __device__ __forceinline__ unsigned pk2(float lo, float hi) { return pg8::cvt_pk_bf16(lo, hi); }
; __device__ __forceinline__ void unpack8(const u32x4 w, float (&f)[8]) { f[0] = bflo(w.x); f[1] = bfhi(w.x); f[2] = bflo(w.y); f[3] = bfhi(w.y); f[4] = bflo(w.z); f[5] = bfhi(w.z); f[6] = bflo(w.w); f[7] = bfhi(w.w); }
;     __device__ __forceinline__ void operator()(const f32x4 (&acc)[2][2][4][2], const Unit& u, int wr, int wc, int fr, int fq) const {
;         const int row0 = u.pm * 256 + wr * 64 + fr, col0 = u.pn * 256 + wc * 32 + 8 * fq;
; #pragma unroll
;         for (int ai = 0; ai < 2; ++ai) {
;             u32x4 braw[4][2];
; #pragma unroll
;             for (int m = 0; m < 4; ++m)
; #pragma unroll
;                 for (int bj = 0; bj < 2; ++bj) braw[m][bj] = *(const u32x4*)(base + (size_t)(row0 + ai * 128 + m * 16) * DM + col0 + bj * 128);
;             __builtin_amdgcn_sched_barrier(0);
; #pragma unroll
;             for (int m = 0; m < 4; ++m) { const int row = row0 + ai * 128 + m * 16; const size_t off = (size_t)row * DM + col0; float sq = 0.f;
; #pragma unroll
;                 for (int bj = 0; bj < 2; ++bj) { float b[8]; unpack8(braw[m][bj], b);
;                     const f32x4 a0 = acc[ai][bj][m][0], a1 = acc[ai][bj][m][1];
;                     const f32x4 v0 = (f32x4){b[0] + a0[0], b[1] + a0[1], b[2] + a0[2], b[3] + a0[3]}, v1 = (f32x4){b[4] + a1[0], b[5] + a1[1], b[6] + a1[2], b[7] + a1[3]};
;                     sq += (v0[0] * v0[0] + v0[1] * v0[1]) + (v0[2] * v0[2] + v0[3] * v0[3]) + (v1[0] * v1[0] + v1[1] * v1[1]) + (v1[2] * v1[2] + v1[3] * v1[3]);
;                     if (Xf) { *(f32x4*)(Xf + off + bj * 128) = v0; *(f32x4*)(Xf + off + bj * 128 + 4) = v1; }
;                     if (XB) { u32x4 w; w.x = pk2(v0[0], v0[1]); w.y = pk2(v0[2], v0[3]); w.z = pk2(v1[0], v1[1]); w.w = pk2(v1[2], v1[3]); *(u32x4*)(XB + off + bj * 128) = w; } }
.LBB0_945:
	v_lshl_add_u32 v194, s29, 8, v206
	v_lshl_or_b32 v190, s28, 8, v208
	v_ashrrev_i32_e32 v191, 31, v190
	v_ashrrev_i32_e32 v195, 31, v194
	v_lshl_add_u64 v[192:193], v[190:191], 1, s[36:37]
	v_lshlrev_b64 v[148:149], 11, v[194:195]
	v_or_b32_e32 v200, 16, v194
	v_lshl_add_u64 v[148:149], v[192:193], 0, v[148:149]
	v_ashrrev_i32_e32 v201, 31, v200
	global_load_dwordx4 v[220:223], v[148:149], off
	global_load_dwordx4 v[172:175], v[148:149], off offset:256
	v_lshlrev_b64 v[148:149], 11, v[200:201]
	v_or_b32_e32 v198, 32, v194
	v_lshl_add_u64 v[148:149], v[192:193], 0, v[148:149]
	v_ashrrev_i32_e32 v199, 31, v198
	global_load_dwordx4 v[168:171], v[148:149], off
	global_load_dwordx4 v[164:167], v[148:149], off offset:256
	v_lshlrev_b64 v[148:149], 11, v[198:199]
	v_or_b32_e32 v196, 48, v194
	v_lshl_add_u64 v[148:149], v[192:193], 0, v[148:149]
	v_ashrrev_i32_e32 v197, 31, v196
	global_load_dwordx4 v[160:163], v[148:149], off
	global_load_dwordx4 v[156:159], v[148:149], off offset:256
	v_lshlrev_b64 v[148:149], 11, v[196:197]
	v_lshl_add_u64 v[148:149], v[192:193], 0, v[148:149]
	global_load_dwordx4 v[152:155], v[148:149], off
	s_nop 0
	global_load_dwordx4 v[148:151], v[148:149], off offset:256
	s_cmp_lg_u64 s[8:9], 0
	s_cbranch_scc1 .Lskpf_g6
	s_and_b32 s98, s2, 7
	s_lshl_b32 s98, s98, 19
	s_add_u32 s98, s98, 0xfb00000
	s_lshr_b32 s99, s2, 3
	s_and_b32 s99, s99, 31
	s_lshl_b32 s99, s99, 14
	s_add_u32 s98, s98, s99
	s_add_u32 s98, s70, s98
	s_addc_u32 s99, s71, 0
	v_and_b32_e32 v240, 127, v184
	v_lshlrev_b32_e32 v240, 7, v240
	v_mov_b32_e32 v241, 0
	v_lshl_add_u64 v[240:241], s[98:99], 0, v[240:241]
	global_load_dword v242, v[240:241], off
.Lskpf_g6:
	v_lshlrev_b64 v[186:187], 10, v[194:195]
	v_lshl_add_u64 v[202:203], v[186:187], 0, v[190:191]
	s_waitcnt vmcnt(0)
	v_lshlrev_b32_e32 v186, 16, v220
	v_and_b32_e32 v187, 0xffff0000, v220
	v_pk_add_f32 v[144:145], v[144:145], v[186:187]
	v_lshlrev_b32_e32 v186, 16, v221
	v_and_b32_e32 v187, 0xffff0000, v221
	v_pk_add_f32 v[146:147], v[146:147], v[186:187]
	v_lshlrev_b32_e32 v186, 16, v222
	v_and_b32_e32 v187, 0xffff0000, v222
	v_pk_add_f32 v[140:141], v[140:141], v[186:187]
	v_lshlrev_b32_e32 v186, 16, v223
	v_and_b32_e32 v187, 0xffff0000, v223
	v_pk_add_f32 v[142:143], v[142:143], v[186:187]
	v_cndmask_b32_e64 v186, 0, 1, s[54:55]
	v_cmp_ne_u32_e64 s[10:11], 1, v186
	s_andn2_b64 vcc, exec, s[54:55]
	v_lshl_add_u64 v[204:205], v[202:203], 2, s[16:17]
	s_cbranch_vccnz .LBB0_947
	global_store_dwordx4 v[204:205], v[144:147], off
	global_store_dwordx4 v[204:205], v[140:143], off offset:16
